# v38 plus removal of the mid-block s_setprio 0/1 pairs
# speedup vs baseline: 1.0040x; 1.0022x over previous
; #define PG8_STAGE(bufoff, gbase, voff) do { _Pragma("unroll") for (int _i = 0; _i < 2; ++_i) \
;         __builtin_amdgcn_global_load_lds((const unsigned*)((const char*)(gbase) + (voff)[_i]), (PG8_LAS unsigned*)(lds + (bufoff) + ldsw + _i * 8192), 16, 0, 0); } while (0)
; #define PG8_LDA(dst, b, h) do { _Pragma("unroll") for (int m = 0; m < 4; ++m) _Pragma("unroll") for (int k = 0; k < 2; ++k) dst[m][k] = *(const PG8_LAS bf16x8*)(lds + PG8_SA(b, h) + aoff + m * 2048 + k * 1024); } while (0)
; #define PG8_LDB(dst, b, h) do { _Pragma("unroll") for (int n = 0; n < 2; ++n) _Pragma("unroll") for (int k = 0; k < 2; ++k) dst[n][k] = *(const PG8_LAS bf16x8*)(lds + PG8_SB(b, h) + boff + n * 2048 + k * 1024); } while (0)
; #define PG8_MMA(ai, bj, At, Bt) do { __builtin_amdgcn_s_setprio(1); _Pragma("unroll") for (int m = 0; m < 4; ++m) _Pragma("unroll") for (int n = 0; n < 2; ++n) _Pragma("unroll") for (int k = 0; k < 2; ++k) \
;         acc[ai][bj][m][n] = __builtin_amdgcn_mfma_f32_16x16x32_bf16(Bt[n][k], At[m][k], acc[ai][bj][m][n], 0, 0, 0); __builtin_amdgcn_s_setprio(0); } while (0)
; #define PG8_WAIT_V(n) asm volatile("s_waitcnt vmcnt(" #n ")" ::: "memory")
; #define PG8_WAIT_L(n) asm volatile("s_waitcnt lgkmcnt(" #n ")" ::: "memory")
; #define PG8_BAR __builtin_amdgcn_s_barrier()
; #define PG8_SCHED __builtin_amdgcn_sched_barrier(0)
; template <class Epi, class Sched, bool ALIGN_EPI = false, bool SP2 = false>
; __device__ __forceinline__ void gemm_phase(PG8_LAS unsigned char* lds, const Gemm g, const Sched& S, const Epi& E) {
;     ...
;             PG8_LDB(B0, 0, 0); PG8_LDB(B1, 0, 1); PG8_SCHED; PG8_LDA(At, 0, 0); PG8_STAGE(PG8_SA(1, 1), a1 + hstep, voffA);
;             PG8_WAIT_V(8); PG8_WAIT_L(0); PG8_BAR; PG8_MMA(0, 0, At, B0); PG8_MMA(0, 1, At, B1); PG8_BAR; PG8_SCHED;
;             PG8_LDA(At, 0, 1); PG8_STAGE(PG8_SB(0, 0), b2, voffB); PG8_STAGE(PG8_SB(0, 1), b2 + hstep, voffB); PG8_STAGE(PG8_SA(0, 0), a2, voffA);
;             PG8_WAIT_V(8); PG8_WAIT_L(0); PG8_BAR; PG8_MMA(1, 0, At, B0); PG8_MMA(1, 1, At, B1); PG8_BAR; PG8_SCHED;
.LBB0_63:
	s_add_i32 s66, s46, 2
	s_add_u32 s10, s44, 0x80
	s_addc_u32 s11, s45, 0
	s_add_i32 s67, 0, 0x10000
	s_cmp_eq_u32 s74, s46
	s_cselect_b64 vcc, -1, 0
	s_cselect_b32 s47, s63, s11
	s_cselect_b32 s46, s62, s10
	s_cselect_b32 s79, s65, s20
	s_cselect_b32 s78, s64, s19
	s_add_i32 s10, 0, 0x14000
	v_add_u32_e32 v140, s67, v183
	v_add_u32_e32 v166, s10, v183
	ds_read_b128 v[128:131], v140
	ds_read_b128 v[132:135], v140 offset:1024
	ds_read_b128 v[136:139], v140 offset:2048
	ds_read_b128 v[140:143], v140 offset:3072
	ds_read_b128 v[144:147], v166
	ds_read_b128 v[148:151], v166 offset:1024
	ds_read_b128 v[152:155], v166 offset:2048
	ds_read_b128 v[166:169], v166 offset:3072
	v_lshl_add_u64 v[190:191], s[44:45], 0, v[162:163]
	s_add_i32 m0, s23, 0xc000
	ds_read_b128 v[170:173], v185
	ds_read_b128 v[174:177], v185 offset:1024
	ds_read_b128 v[178:181], v185 offset:2048
	ds_read_b128 v[186:189], v185 offset:3072
	ds_read_b128 v[194:197], v185 offset:4096
	ds_read_b128 v[198:201], v185 offset:5120
	ds_read_b128 v[202:205], v185 offset:6144
	ds_read_b128 v[206:209], v185 offset:7168
	global_load_lds_dwordx4 v[190:191], off
	v_lshl_add_u64 v[190:191], s[44:45], 0, v[164:165]
	s_add_i32 m0, s23, 0xe000
	s_nop 0
	global_load_lds_dwordx4 v[190:191], off
	s_waitcnt vmcnt(8)
	s_waitcnt lgkmcnt(0)
	s_setprio 1
	s_barrier
	v_mfma_f32_16x16x32_bf16 v[124:127], v[128:131], v[170:173], v[124:127]
	v_mfma_f32_16x16x32_bf16 v[120:123], v[136:139], v[170:173], v[120:123]
	v_mfma_f32_16x16x32_bf16 v[108:111], v[128:131], v[178:181], v[108:111]
	v_mfma_f32_16x16x32_bf16 v[104:107], v[136:139], v[178:181], v[104:107]
	v_mfma_f32_16x16x32_bf16 v[92:95], v[128:131], v[194:197], v[92:95]
	v_mfma_f32_16x16x32_bf16 v[88:91], v[136:139], v[194:197], v[88:91]
	v_mfma_f32_16x16x32_bf16 v[76:79], v[128:131], v[202:205], v[76:79]
	v_mfma_f32_16x16x32_bf16 v[72:75], v[136:139], v[202:205], v[72:75]
	v_mfma_f32_16x16x32_bf16 v[124:127], v[132:135], v[174:177], v[124:127]
	v_mfma_f32_16x16x32_bf16 v[120:123], v[140:143], v[174:177], v[120:123]
	v_mfma_f32_16x16x32_bf16 v[108:111], v[132:135], v[186:189], v[108:111]
	v_mfma_f32_16x16x32_bf16 v[104:107], v[140:143], v[186:189], v[104:107]
	v_mfma_f32_16x16x32_bf16 v[92:95], v[132:135], v[198:201], v[92:95]
	v_mfma_f32_16x16x32_bf16 v[88:91], v[140:143], v[198:201], v[88:91]
	v_mfma_f32_16x16x32_bf16 v[76:79], v[132:135], v[206:209], v[76:79]
	v_mfma_f32_16x16x32_bf16 v[72:75], v[140:143], v[206:209], v[72:75]
	v_mfma_f32_16x16x32_bf16 v[116:119], v[144:147], v[170:173], v[116:119]
	v_mfma_f32_16x16x32_bf16 v[112:115], v[152:155], v[170:173], v[112:115]
	v_mfma_f32_16x16x32_bf16 v[100:103], v[144:147], v[178:181], v[100:103]
	v_mfma_f32_16x16x32_bf16 v[96:99], v[152:155], v[178:181], v[96:99]
	v_mfma_f32_16x16x32_bf16 v[84:87], v[144:147], v[194:197], v[84:87]
	v_mfma_f32_16x16x32_bf16 v[80:83], v[152:155], v[194:197], v[80:83]
	v_mfma_f32_16x16x32_bf16 v[68:71], v[144:147], v[202:205], v[68:71]
	v_mfma_f32_16x16x32_bf16 v[64:67], v[152:155], v[202:205], v[64:67]
	v_mfma_f32_16x16x32_bf16 v[116:119], v[148:151], v[174:177], v[116:119]
	v_mfma_f32_16x16x32_bf16 v[112:115], v[166:169], v[174:177], v[112:115]
	v_mfma_f32_16x16x32_bf16 v[100:103], v[148:151], v[186:189], v[100:103]
	v_mfma_f32_16x16x32_bf16 v[96:99], v[166:169], v[186:189], v[96:99]
	v_mfma_f32_16x16x32_bf16 v[84:87], v[148:151], v[198:201], v[84:87]
	v_mfma_f32_16x16x32_bf16 v[80:83], v[166:169], v[198:201], v[80:83]
	v_mfma_f32_16x16x32_bf16 v[68:71], v[148:151], v[206:209], v[68:71]
	v_mfma_f32_16x16x32_bf16 v[64:67], v[166:169], v[206:209], v[64:67]
	s_barrier
	s_setprio 0
	s_add_i32 s11, s67, s22
	v_lshl_add_u64 v[190:191], s[78:79], 0, v[192:193]
	s_mov_b32 m0, s11
	ds_read_b128 v[170:173], v185 offset:16384
	ds_read_b128 v[174:177], v185 offset:17408
	ds_read_b128 v[178:181], v185 offset:18432
	ds_read_b128 v[186:189], v185 offset:19456
	ds_read_b128 v[194:197], v185 offset:20480
	ds_read_b128 v[198:201], v185 offset:21504
	ds_read_b128 v[202:205], v185 offset:22528
	ds_read_b128 v[206:209], v185 offset:23552
	global_load_lds_dwordx4 v[190:191], off
	s_add_i32 m0, s11, 0x2000
	v_lshl_add_u64 v[210:211], s[78:79], 0, v[160:161]
	s_add_u32 s78, s78, s52
	s_addc_u32 s79, s79, 0
	s_add_i32 s10, s10, s22
	global_load_lds_dwordx4 v[210:211], off
	v_lshl_add_u64 v[212:213], s[78:79], 0, v[192:193]
	s_mov_b32 m0, s10
	v_lshl_add_u64 v[214:215], s[78:79], 0, v[160:161]
	global_load_lds_dwordx4 v[212:213], off
	s_add_i32 m0, s10, 0x2000
	v_lshl_add_u64 v[216:217], s[46:47], 0, v[156:157]
	global_load_lds_dwordx4 v[214:215], off
	s_mov_b32 m0, s23
	v_lshl_add_u64 v[218:219], s[46:47], 0, v[158:159]
	global_load_lds_dwordx4 v[216:217], off
	s_mov_b32 m0, s51
	s_nop 0
	global_load_lds_dwordx4 v[218:219], off
	s_waitcnt vmcnt(8)
	s_waitcnt lgkmcnt(0)
	s_setprio 1
	s_barrier
; #define PG8_STAGE(bufoff, gbase, voff) do { _Pragma("unroll") for (int _i = 0; _i < 2; ++_i) \
;         __builtin_amdgcn_global_load_lds((const unsigned*)((const char*)(gbase) + (voff)[_i]), (PG8_LAS unsigned*)(lds + (bufoff) + ldsw + _i * 8192), 16, 0, 0); } while (0)
; #define PG8_LDA(dst, b, h) do { _Pragma("unroll") for (int m = 0; m < 4; ++m) _Pragma("unroll") for (int k = 0; k < 2; ++k) dst[m][k] = *(const PG8_LAS bf16x8*)(lds + PG8_SA(b, h) + aoff + m * 2048 + k * 1024); } while (0)
; #define PG8_LDB(dst, b, h) do { _Pragma("unroll") for (int n = 0; n < 2; ++n) _Pragma("unroll") for (int k = 0; k < 2; ++k) dst[n][k] = *(const PG8_LAS bf16x8*)(lds + PG8_SB(b, h) + boff + n * 2048 + k * 1024); } while (0)
; #define PG8_MMA(ai, bj, At, Bt) do { __builtin_amdgcn_s_setprio(1); _Pragma("unroll") for (int m = 0; m < 4; ++m) _Pragma("unroll") for (int n = 0; n < 2; ++n) _Pragma("unroll") for (int k = 0; k < 2; ++k) \
;         acc[ai][bj][m][n] = __builtin_amdgcn_mfma_f32_16x16x32_bf16(Bt[n][k], At[m][k], acc[ai][bj][m][n], 0, 0, 0); __builtin_amdgcn_s_setprio(0); } while (0)
; #define PG8_WAIT_V(n) asm volatile("s_waitcnt vmcnt(" #n ")" ::: "memory")
; #define PG8_WAIT_L(n) asm volatile("s_waitcnt lgkmcnt(" #n ")" ::: "memory")
; #define PG8_BAR __builtin_amdgcn_s_barrier()
; #define PG8_SCHED __builtin_amdgcn_sched_barrier(0)
; template <class Epi, class Sched, bool ALIGN_EPI = false, bool SP2 = false>
; __device__ __forceinline__ void gemm_phase(PG8_LAS unsigned char* lds, const Gemm g, const Sched& S, const Epi& E) {
;     ...
;             PG8_WAIT_V(8); PG8_WAIT_L(0); PG8_BAR; PG8_MMA(1, 0, At, B0); PG8_MMA(1, 1, At, B1); PG8_BAR; PG8_SCHED;
;             PG8_LDB(B0, 1, 0); PG8_LDB(B1, 1, 1); PG8_SCHED; PG8_LDA(At, 1, 0); PG8_STAGE(PG8_SA(0, 1), a2 + hstep, voffA);
;             PG8_WAIT_V(8); PG8_WAIT_L(0); PG8_BAR; PG8_MMA(0, 0, At, B0); PG8_MMA(0, 1, At, B1); PG8_BAR; PG8_SCHED;
	v_mfma_f32_16x16x32_bf16 v[60:63], v[128:131], v[170:173], v[60:63]
	v_mfma_f32_16x16x32_bf16 v[56:59], v[136:139], v[170:173], v[56:59]
	v_mfma_f32_16x16x32_bf16 v[44:47], v[128:131], v[178:181], v[44:47]
	v_mfma_f32_16x16x32_bf16 v[40:43], v[136:139], v[178:181], v[40:43]
	v_mfma_f32_16x16x32_bf16 v[28:31], v[128:131], v[194:197], v[28:31]
	v_mfma_f32_16x16x32_bf16 v[24:27], v[136:139], v[194:197], v[24:27]
	v_mfma_f32_16x16x32_bf16 v[12:15], v[128:131], v[202:205], v[12:15]
	v_mfma_f32_16x16x32_bf16 v[8:11], v[136:139], v[202:205], v[8:11]
	v_mfma_f32_16x16x32_bf16 v[60:63], v[132:135], v[174:177], v[60:63]
	v_mfma_f32_16x16x32_bf16 v[56:59], v[140:143], v[174:177], v[56:59]
	v_mfma_f32_16x16x32_bf16 v[44:47], v[132:135], v[186:189], v[44:47]
	v_mfma_f32_16x16x32_bf16 v[40:43], v[140:143], v[186:189], v[40:43]
	v_mfma_f32_16x16x32_bf16 v[28:31], v[132:135], v[198:201], v[28:31]
	v_mfma_f32_16x16x32_bf16 v[24:27], v[140:143], v[198:201], v[24:27]
	v_mfma_f32_16x16x32_bf16 v[12:15], v[132:135], v[206:209], v[12:15]
	v_mfma_f32_16x16x32_bf16 v[8:11], v[140:143], v[206:209], v[8:11]
	v_mfma_f32_16x16x32_bf16 v[52:55], v[144:147], v[170:173], v[52:55]
	v_mfma_f32_16x16x32_bf16 v[48:51], v[152:155], v[170:173], v[48:51]
	v_mfma_f32_16x16x32_bf16 v[36:39], v[144:147], v[178:181], v[36:39]
	v_mfma_f32_16x16x32_bf16 v[32:35], v[152:155], v[178:181], v[32:35]
	v_mfma_f32_16x16x32_bf16 v[20:23], v[144:147], v[194:197], v[20:23]
	v_mfma_f32_16x16x32_bf16 v[16:19], v[152:155], v[194:197], v[16:19]
	v_mfma_f32_16x16x32_bf16 v[4:7], v[144:147], v[202:205], v[4:7]
	v_mfma_f32_16x16x32_bf16 v[0:3], v[152:155], v[202:205], v[0:3]
	v_mfma_f32_16x16x32_bf16 v[52:55], v[148:151], v[174:177], v[52:55]
	v_mfma_f32_16x16x32_bf16 v[48:51], v[166:169], v[174:177], v[48:51]
	v_mfma_f32_16x16x32_bf16 v[36:39], v[148:151], v[186:189], v[36:39]
	v_mfma_f32_16x16x32_bf16 v[32:35], v[166:169], v[186:189], v[32:35]
	v_mfma_f32_16x16x32_bf16 v[20:23], v[148:151], v[198:201], v[20:23]
	v_mfma_f32_16x16x32_bf16 v[16:19], v[166:169], v[198:201], v[16:19]
	v_mfma_f32_16x16x32_bf16 v[4:7], v[148:151], v[206:209], v[4:7]
	v_mfma_f32_16x16x32_bf16 v[0:3], v[166:169], v[206:209], v[0:3]
	s_barrier
	s_setprio 0
	s_add_i32 s10, 0, 0x18000
	s_add_i32 s11, 0, 0x1c000
	v_add_u32_e32 v140, s10, v183
	v_add_u32_e32 v166, s11, v183
	ds_read_b128 v[128:131], v140
	ds_read_b128 v[132:135], v140 offset:1024
	ds_read_b128 v[136:139], v140 offset:2048
	ds_read_b128 v[140:143], v140 offset:3072
	ds_read_b128 v[144:147], v166
	ds_read_b128 v[148:151], v166 offset:1024
	ds_read_b128 v[152:155], v166 offset:2048
	ds_read_b128 v[166:169], v166 offset:3072
	s_add_u32 s46, s46, s52
	s_addc_u32 s47, s47, 0
	s_mov_b32 m0, s68
	v_lshl_add_u64 v[220:221], s[46:47], 0, v[156:157]
	ds_read_b128 v[170:173], v185 offset:32768
	ds_read_b128 v[174:177], v185 offset:33792
	ds_read_b128 v[178:181], v185 offset:34816
	ds_read_b128 v[186:189], v185 offset:35840
	ds_read_b128 v[194:197], v185 offset:36864
	ds_read_b128 v[198:201], v185 offset:37888
	ds_read_b128 v[202:205], v185 offset:38912
	ds_read_b128 v[206:209], v185 offset:39936
	global_load_lds_dwordx4 v[220:221], off
	v_lshl_add_u64 v[220:221], s[46:47], 0, v[158:159]
	s_mov_b32 m0, s69
	s_nop 0
	global_load_lds_dwordx4 v[220:221], off
	s_waitcnt vmcnt(8)
	s_waitcnt lgkmcnt(0)
	s_setprio 1
	s_barrier
	v_mfma_f32_16x16x32_bf16 v[124:127], v[128:131], v[170:173], v[124:127]
	v_mfma_f32_16x16x32_bf16 v[120:123], v[136:139], v[170:173], v[120:123]
	v_mfma_f32_16x16x32_bf16 v[108:111], v[128:131], v[178:181], v[108:111]
	v_mfma_f32_16x16x32_bf16 v[104:107], v[136:139], v[178:181], v[104:107]
	v_mfma_f32_16x16x32_bf16 v[92:95], v[128:131], v[194:197], v[92:95]
	v_mfma_f32_16x16x32_bf16 v[88:91], v[136:139], v[194:197], v[88:91]
	v_mfma_f32_16x16x32_bf16 v[76:79], v[128:131], v[202:205], v[76:79]
	v_mfma_f32_16x16x32_bf16 v[72:75], v[136:139], v[202:205], v[72:75]
	v_mfma_f32_16x16x32_bf16 v[124:127], v[132:135], v[174:177], v[124:127]
	v_mfma_f32_16x16x32_bf16 v[120:123], v[140:143], v[174:177], v[120:123]
	v_mfma_f32_16x16x32_bf16 v[108:111], v[132:135], v[186:189], v[108:111]
	v_mfma_f32_16x16x32_bf16 v[104:107], v[140:143], v[186:189], v[104:107]
	v_mfma_f32_16x16x32_bf16 v[92:95], v[132:135], v[198:201], v[92:95]
	v_mfma_f32_16x16x32_bf16 v[88:91], v[140:143], v[198:201], v[88:91]
	v_mfma_f32_16x16x32_bf16 v[76:79], v[132:135], v[206:209], v[76:79]
	v_mfma_f32_16x16x32_bf16 v[72:75], v[140:143], v[206:209], v[72:75]
	v_mfma_f32_16x16x32_bf16 v[116:119], v[144:147], v[170:173], v[116:119]
	v_mfma_f32_16x16x32_bf16 v[112:115], v[152:155], v[170:173], v[112:115]
	v_mfma_f32_16x16x32_bf16 v[100:103], v[144:147], v[178:181], v[100:103]
	v_mfma_f32_16x16x32_bf16 v[96:99], v[152:155], v[178:181], v[96:99]
	v_mfma_f32_16x16x32_bf16 v[84:87], v[144:147], v[194:197], v[84:87]
	v_mfma_f32_16x16x32_bf16 v[80:83], v[152:155], v[194:197], v[80:83]
	v_mfma_f32_16x16x32_bf16 v[68:71], v[144:147], v[202:205], v[68:71]
	v_mfma_f32_16x16x32_bf16 v[64:67], v[152:155], v[202:205], v[64:67]
	v_mfma_f32_16x16x32_bf16 v[116:119], v[148:151], v[174:177], v[116:119]
	v_mfma_f32_16x16x32_bf16 v[112:115], v[166:169], v[174:177], v[112:115]
	v_mfma_f32_16x16x32_bf16 v[100:103], v[148:151], v[186:189], v[100:103]
	v_mfma_f32_16x16x32_bf16 v[96:99], v[166:169], v[186:189], v[96:99]
	v_mfma_f32_16x16x32_bf16 v[84:87], v[148:151], v[198:201], v[84:87]
	v_mfma_f32_16x16x32_bf16 v[80:83], v[166:169], v[198:201], v[80:83]
	v_mfma_f32_16x16x32_bf16 v[68:71], v[148:151], v[206:209], v[68:71]
	v_mfma_f32_16x16x32_bf16 v[64:67], v[166:169], v[206:209], v[64:67]
	s_barrier
; #define PG8_STAGE(bufoff, gbase, voff) do { _Pragma("unroll") for (int _i = 0; _i < 2; ++_i) \
;         __builtin_amdgcn_global_load_lds((const unsigned*)((const char*)(gbase) + (voff)[_i]), (PG8_LAS unsigned*)(lds + (bufoff) + ldsw + _i * 8192), 16, 0, 0); } while (0)
; #define PG8_LDA(dst, b, h) do { _Pragma("unroll") for (int m = 0; m < 4; ++m) _Pragma("unroll") for (int k = 0; k < 2; ++k) dst[m][k] = *(const PG8_LAS bf16x8*)(lds + PG8_SA(b, h) + aoff + m * 2048 + k * 1024); } while (0)
; #define PG8_MMA(ai, bj, At, Bt) do { __builtin_amdgcn_s_setprio(1); _Pragma("unroll") for (int m = 0; m < 4; ++m) _Pragma("unroll") for (int n = 0; n < 2; ++n) _Pragma("unroll") for (int k = 0; k < 2; ++k) \
;         acc[ai][bj][m][n] = __builtin_amdgcn_mfma_f32_16x16x32_bf16(Bt[n][k], At[m][k], acc[ai][bj][m][n], 0, 0, 0); __builtin_amdgcn_s_setprio(0); } while (0)
; #define PG8_WAIT_V(n) asm volatile("s_waitcnt vmcnt(" #n ")" ::: "memory")
; #define PG8_WAIT_L(n) asm volatile("s_waitcnt lgkmcnt(" #n ")" ::: "memory")
; #define PG8_BAR __builtin_amdgcn_s_barrier()
; #define PG8_SCHED __builtin_amdgcn_sched_barrier(0)
; template <class Epi, class Sched, bool ALIGN_EPI = false, bool SP2 = false>
; __device__ __forceinline__ void gemm_phase(PG8_LAS unsigned char* lds, const Gemm g, const Sched& S, const Epi& E) {
;     ...
;         for (int t = 0; t < nt; t += 2) {
;             const bool last = (t == nt - 2);
;             const char* a1 = cA + (size_t)(t + 1) * kstep;
;             const char* a2 = last ? nA : cA + (size_t)(t + 2) * kstep; const char* b2 = last ? nB : cB + (size_t)(t + 2) * kstep;
;             const char* a3 = a2 + kstep; const char* b3 = b2 + kstep;
;     ...
;             PG8_LDA(At, 1, 1); PG8_STAGE(PG8_SB(1, 0), b3, voffB); PG8_STAGE(PG8_SB(1, 1), b3 + hstep, voffB); PG8_STAGE(PG8_SA(1, 0), a3, voffA);
;             PG8_WAIT_V(8); PG8_WAIT_L(0); PG8_BAR; PG8_MMA(1, 0, At, B0); PG8_MMA(1, 1, At, B1); PG8_BAR; PG8_SCHED;
	s_setprio 0
	s_add_i32 s10, s10, s22
	v_lshl_add_u64 v[190:191], v[190:191], 0, s[36:37]
	s_mov_b32 m0, s10
	ds_read_b128 v[170:173], v185 offset:49152
	ds_read_b128 v[174:177], v185 offset:50176
	ds_read_b128 v[178:181], v185 offset:51200
	ds_read_b128 v[186:189], v185 offset:52224
	ds_read_b128 v[194:197], v185 offset:53248
	ds_read_b128 v[198:201], v185 offset:54272
	ds_read_b128 v[202:205], v185 offset:55296
	ds_read_b128 v[206:209], v185 offset:56320
	global_load_lds_dwordx4 v[190:191], off
	v_lshl_add_u64 v[190:191], v[210:211], 0, s[36:37]
	s_add_i32 m0, s10, 0x2000
	s_add_i32 s10, s11, s22
	global_load_lds_dwordx4 v[190:191], off
	v_lshl_add_u64 v[190:191], v[212:213], 0, s[36:37]
	s_mov_b32 m0, s10
	s_nop 0
	global_load_lds_dwordx4 v[190:191], off
	v_lshl_add_u64 v[190:191], v[214:215], 0, s[36:37]
	s_add_i32 m0, s10, 0x2000
	s_nop 0
	global_load_lds_dwordx4 v[190:191], off
	v_lshl_add_u64 v[190:191], v[216:217], 0, s[36:37]
	s_mov_b32 m0, s70
	s_nop 0
	global_load_lds_dwordx4 v[190:191], off
	v_lshl_add_u64 v[190:191], v[218:219], 0, s[36:37]
	s_mov_b32 m0, s71
	s_nop 0
	global_load_lds_dwordx4 v[190:191], off
	s_waitcnt vmcnt(8)
	s_waitcnt lgkmcnt(0)
	s_setprio 1
	s_barrier
	v_mfma_f32_16x16x32_bf16 v[60:63], v[128:131], v[170:173], v[60:63]
	v_mfma_f32_16x16x32_bf16 v[56:59], v[136:139], v[170:173], v[56:59]
	v_mfma_f32_16x16x32_bf16 v[44:47], v[128:131], v[178:181], v[44:47]
	v_mfma_f32_16x16x32_bf16 v[40:43], v[136:139], v[178:181], v[40:43]
	v_mfma_f32_16x16x32_bf16 v[28:31], v[128:131], v[194:197], v[28:31]
	v_mfma_f32_16x16x32_bf16 v[24:27], v[136:139], v[194:197], v[24:27]
	v_mfma_f32_16x16x32_bf16 v[12:15], v[128:131], v[202:205], v[12:15]
	v_mfma_f32_16x16x32_bf16 v[8:11], v[136:139], v[202:205], v[8:11]
	v_mfma_f32_16x16x32_bf16 v[60:63], v[132:135], v[174:177], v[60:63]
	v_mfma_f32_16x16x32_bf16 v[56:59], v[140:143], v[174:177], v[56:59]
	v_mfma_f32_16x16x32_bf16 v[44:47], v[132:135], v[186:189], v[44:47]
	v_mfma_f32_16x16x32_bf16 v[40:43], v[140:143], v[186:189], v[40:43]
	v_mfma_f32_16x16x32_bf16 v[28:31], v[132:135], v[198:201], v[28:31]
	v_mfma_f32_16x16x32_bf16 v[24:27], v[140:143], v[198:201], v[24:27]
	v_mfma_f32_16x16x32_bf16 v[12:15], v[132:135], v[206:209], v[12:15]
	v_mfma_f32_16x16x32_bf16 v[8:11], v[140:143], v[206:209], v[8:11]
	v_mfma_f32_16x16x32_bf16 v[52:55], v[144:147], v[170:173], v[52:55]
	v_mfma_f32_16x16x32_bf16 v[48:51], v[152:155], v[170:173], v[48:51]
	v_mfma_f32_16x16x32_bf16 v[36:39], v[144:147], v[178:181], v[36:39]
	v_mfma_f32_16x16x32_bf16 v[32:35], v[152:155], v[178:181], v[32:35]
	v_mfma_f32_16x16x32_bf16 v[20:23], v[144:147], v[194:197], v[20:23]
	v_mfma_f32_16x16x32_bf16 v[16:19], v[152:155], v[194:197], v[16:19]
	v_mfma_f32_16x16x32_bf16 v[4:7], v[144:147], v[202:205], v[4:7]
	v_mfma_f32_16x16x32_bf16 v[0:3], v[152:155], v[202:205], v[0:3]
	v_mfma_f32_16x16x32_bf16 v[52:55], v[148:151], v[174:177], v[52:55]
	v_mfma_f32_16x16x32_bf16 v[48:51], v[166:169], v[174:177], v[48:51]
	v_mfma_f32_16x16x32_bf16 v[36:39], v[148:151], v[186:189], v[36:39]
	v_mfma_f32_16x16x32_bf16 v[32:35], v[166:169], v[186:189], v[32:35]
	v_mfma_f32_16x16x32_bf16 v[20:23], v[148:151], v[198:201], v[20:23]
	v_mfma_f32_16x16x32_bf16 v[16:19], v[166:169], v[198:201], v[16:19]
	v_mfma_f32_16x16x32_bf16 v[4:7], v[148:151], v[206:209], v[4:7]
	v_mfma_f32_16x16x32_bf16 v[0:3], v[166:169], v[206:209], v[0:3]
	s_cbranch_vccnz .Llast2_g1
	s_barrier
	s_setprio 0
	s_add_u32 s44, s44, 0x100
	s_addc_u32 s45, s45, 0
	s_add_u32 s19, s19, 0x100
	s_addc_u32 s20, s20, 0
	s_cmp_ge_u32 s66, s73
	s_mov_b32 s46, s66
	s_branch .LBB0_63

; #define PG8_STAGE(bufoff, gbase, voff) do { _Pragma("unroll") for (int _i = 0; _i < 2; ++_i) \
;         __builtin_amdgcn_global_load_lds((const unsigned*)((const char*)(gbase) + (voff)[_i]), (PG8_LAS unsigned*)(lds + (bufoff) + ldsw + _i * 8192), 16, 0, 0); } while (0)
; #define PG8_LDA(dst, b, h) do { _Pragma("unroll") for (int m = 0; m < 4; ++m) _Pragma("unroll") for (int k = 0; k < 2; ++k) dst[m][k] = *(const PG8_LAS bf16x8*)(lds + PG8_SA(b, h) + aoff + m * 2048 + k * 1024); } while (0)
; #define PG8_LDB(dst, b, h) do { _Pragma("unroll") for (int n = 0; n < 2; ++n) _Pragma("unroll") for (int k = 0; k < 2; ++k) dst[n][k] = *(const PG8_LAS bf16x8*)(lds + PG8_SB(b, h) + boff + n * 2048 + k * 1024); } while (0)
; #define PG8_MMA(ai, bj, At, Bt) do { __builtin_amdgcn_s_setprio(1); _Pragma("unroll") for (int m = 0; m < 4; ++m) _Pragma("unroll") for (int n = 0; n < 2; ++n) _Pragma("unroll") for (int k = 0; k < 2; ++k) \
;         acc[ai][bj][m][n] = __builtin_amdgcn_mfma_f32_16x16x32_bf16(Bt[n][k], At[m][k], acc[ai][bj][m][n], 0, 0, 0); __builtin_amdgcn_s_setprio(0); } while (0)
; #define PG8_WAIT_V(n) asm volatile("s_waitcnt vmcnt(" #n ")" ::: "memory")
; #define PG8_WAIT_L(n) asm volatile("s_waitcnt lgkmcnt(" #n ")" ::: "memory")
; #define PG8_BAR __builtin_amdgcn_s_barrier()
; #define PG8_SCHED __builtin_amdgcn_sched_barrier(0)
; template <class Epi, class Sched, bool ALIGN_EPI = false, bool SP2 = false>
; __device__ __forceinline__ void gemm_phase(PG8_LAS unsigned char* lds, const Gemm g, const Sched& S, const Epi& E) {
;     ...
;             PG8_LDB(B0, 0, 0); PG8_LDB(B1, 0, 1); PG8_SCHED; PG8_LDA(At, 0, 0); PG8_STAGE(PG8_SA(1, 1), a1 + hstep, voffA);
;             PG8_WAIT_V(8); PG8_WAIT_L(0); PG8_BAR; PG8_MMA(0, 0, At, B0); PG8_MMA(0, 1, At, B1); PG8_BAR; PG8_SCHED;
;             PG8_LDA(At, 0, 1); PG8_STAGE(PG8_SB(0, 0), b2, voffB); PG8_STAGE(PG8_SB(0, 1), b2 + hstep, voffB); PG8_STAGE(PG8_SA(0, 0), a2, voffA);
;             PG8_WAIT_V(8); PG8_WAIT_L(0); PG8_BAR; PG8_MMA(1, 0, At, B0); PG8_MMA(1, 1, At, B1); PG8_BAR; PG8_SCHED;
.LBB0_200:
	s_add_u32 s10, s56, 0xfffc0080
	s_addc_u32 s11, s57, -1
	s_add_i32 s77, 0, 0x10000
	s_cmp_eq_u32 s76, 12
	s_cselect_b64 vcc, -1, 0
	s_cselect_b32 s61, s18, s11
	s_cselect_b32 s60, s19, s10
	s_cselect_b32 s59, s20, s51
	s_cselect_b32 s58, s43, s49
	s_add_i32 s10, 0, 0x14000
	v_add_u32_e32 v140, s77, v163
	v_add_u32_e32 v162, s10, v163
	ds_read_b128 v[128:131], v140
	ds_read_b128 v[132:135], v140 offset:1024
	ds_read_b128 v[136:139], v140 offset:2048
	ds_read_b128 v[140:143], v140 offset:3072
	ds_read_b128 v[166:169], v162
	ds_read_b128 v[170:173], v162 offset:1024
	ds_read_b128 v[174:177], v162 offset:2048
	ds_read_b128 v[178:181], v162 offset:3072
	v_lshl_add_u64 v[190:191], s[56:57], 0, v[158:159]
	s_add_i32 m0, s64, 0xc000
	ds_read_b128 v[182:185], v165
	ds_read_b128 v[186:189], v165 offset:1024
	ds_read_b128 v[194:197], v165 offset:2048
	ds_read_b128 v[198:201], v165 offset:3072
	ds_read_b128 v[202:205], v165 offset:4096
	ds_read_b128 v[206:209], v165 offset:5120
	ds_read_b128 v[210:213], v165 offset:6144
	ds_read_b128 v[214:217], v165 offset:7168
	global_load_lds_dwordx4 v[190:191], off
	v_lshl_add_u64 v[190:191], s[56:57], 0, v[160:161]
	s_add_i32 m0, s64, 0xe000
	s_nop 0
	global_load_lds_dwordx4 v[190:191], off
	s_waitcnt vmcnt(8)
	s_waitcnt lgkmcnt(0)
	s_setprio 1
	s_barrier
	v_mfma_f32_16x16x32_bf16 v[124:127], v[128:131], v[182:185], v[124:127]
	v_mfma_f32_16x16x32_bf16 v[120:123], v[136:139], v[182:185], v[120:123]
	v_mfma_f32_16x16x32_bf16 v[112:115], v[128:131], v[194:197], v[112:115]
	v_mfma_f32_16x16x32_bf16 v[104:107], v[136:139], v[194:197], v[104:107]
	v_mfma_f32_16x16x32_bf16 v[96:99], v[128:131], v[202:205], v[96:99]
	v_mfma_f32_16x16x32_bf16 v[88:91], v[136:139], v[202:205], v[88:91]
	v_mfma_f32_16x16x32_bf16 v[80:83], v[128:131], v[210:213], v[80:83]
	v_mfma_f32_16x16x32_bf16 v[72:75], v[136:139], v[210:213], v[72:75]
	v_mfma_f32_16x16x32_bf16 v[124:127], v[132:135], v[186:189], v[124:127]
	v_mfma_f32_16x16x32_bf16 v[120:123], v[140:143], v[186:189], v[120:123]
	v_mfma_f32_16x16x32_bf16 v[112:115], v[132:135], v[198:201], v[112:115]
	v_mfma_f32_16x16x32_bf16 v[104:107], v[140:143], v[198:201], v[104:107]
	v_mfma_f32_16x16x32_bf16 v[96:99], v[132:135], v[206:209], v[96:99]
	v_mfma_f32_16x16x32_bf16 v[88:91], v[140:143], v[206:209], v[88:91]
	v_mfma_f32_16x16x32_bf16 v[80:83], v[132:135], v[214:217], v[80:83]
	v_mfma_f32_16x16x32_bf16 v[72:75], v[140:143], v[214:217], v[72:75]
	v_mfma_f32_16x16x32_bf16 v[116:119], v[166:169], v[182:185], v[116:119]
	v_mfma_f32_16x16x32_bf16 v[108:111], v[174:177], v[182:185], v[108:111]
	v_mfma_f32_16x16x32_bf16 v[100:103], v[166:169], v[194:197], v[100:103]
	v_mfma_f32_16x16x32_bf16 v[92:95], v[174:177], v[194:197], v[92:95]
	v_mfma_f32_16x16x32_bf16 v[84:87], v[166:169], v[202:205], v[84:87]
	v_mfma_f32_16x16x32_bf16 v[76:79], v[174:177], v[202:205], v[76:79]
	v_mfma_f32_16x16x32_bf16 v[68:71], v[166:169], v[210:213], v[68:71]
	v_mfma_f32_16x16x32_bf16 v[64:67], v[174:177], v[210:213], v[64:67]
	v_mfma_f32_16x16x32_bf16 v[116:119], v[170:173], v[186:189], v[116:119]
	v_mfma_f32_16x16x32_bf16 v[108:111], v[178:181], v[186:189], v[108:111]
	v_mfma_f32_16x16x32_bf16 v[100:103], v[170:173], v[198:201], v[100:103]
	v_mfma_f32_16x16x32_bf16 v[92:95], v[178:181], v[198:201], v[92:95]
	v_mfma_f32_16x16x32_bf16 v[84:87], v[170:173], v[206:209], v[84:87]
	v_mfma_f32_16x16x32_bf16 v[76:79], v[178:181], v[206:209], v[76:79]
	v_mfma_f32_16x16x32_bf16 v[68:71], v[170:173], v[214:217], v[68:71]
	v_mfma_f32_16x16x32_bf16 v[64:67], v[178:181], v[214:217], v[64:67]
	s_barrier
	s_setprio 0
	s_add_i32 s11, s77, s63
	v_lshl_add_u64 v[190:191], s[58:59], 0, v[146:147]
	s_mov_b32 m0, s11
	ds_read_b128 v[182:185], v165 offset:16384
	ds_read_b128 v[186:189], v165 offset:17408
	ds_read_b128 v[194:197], v165 offset:18432
	ds_read_b128 v[198:201], v165 offset:19456
	ds_read_b128 v[202:205], v165 offset:20480
	ds_read_b128 v[206:209], v165 offset:21504
	ds_read_b128 v[210:213], v165 offset:22528
	ds_read_b128 v[214:217], v165 offset:23552
	global_load_lds_dwordx4 v[190:191], off
	s_add_i32 m0, s11, 0x2000
	s_add_u32 s78, s58, 0x40000
	v_lshl_add_u64 v[218:219], s[58:59], 0, v[150:151]
	s_addc_u32 s79, s59, 0
	s_add_i32 s10, s10, s63
	global_load_lds_dwordx4 v[218:219], off
	v_lshl_add_u64 v[220:221], s[78:79], 0, v[146:147]
	s_mov_b32 m0, s10
	v_lshl_add_u64 v[222:223], s[60:61], 0, v[148:149]
	global_load_lds_dwordx4 v[220:221], off
	v_lshl_add_u64 v[220:221], s[78:79], 0, v[150:151]
	s_add_i32 m0, s10, 0x2000
	s_nop 0
	global_load_lds_dwordx4 v[220:221], off
	v_lshl_add_u64 v[220:221], s[60:61], 0, v[144:145]
	s_mov_b32 m0, s64
	s_nop 0
	global_load_lds_dwordx4 v[220:221], off
	s_mov_b32 m0, s65
	s_nop 0
	global_load_lds_dwordx4 v[222:223], off
	s_waitcnt vmcnt(8)
	s_waitcnt lgkmcnt(0)
	s_setprio 1
	s_barrier
; #define PG8_STAGE(bufoff, gbase, voff) do { _Pragma("unroll") for (int _i = 0; _i < 2; ++_i) \
;         __builtin_amdgcn_global_load_lds((const unsigned*)((const char*)(gbase) + (voff)[_i]), (PG8_LAS unsigned*)(lds + (bufoff) + ldsw + _i * 8192), 16, 0, 0); } while (0)
; #define PG8_LDA(dst, b, h) do { _Pragma("unroll") for (int m = 0; m < 4; ++m) _Pragma("unroll") for (int k = 0; k < 2; ++k) dst[m][k] = *(const PG8_LAS bf16x8*)(lds + PG8_SA(b, h) + aoff + m * 2048 + k * 1024); } while (0)
; #define PG8_LDB(dst, b, h) do { _Pragma("unroll") for (int n = 0; n < 2; ++n) _Pragma("unroll") for (int k = 0; k < 2; ++k) dst[n][k] = *(const PG8_LAS bf16x8*)(lds + PG8_SB(b, h) + boff + n * 2048 + k * 1024); } while (0)
; #define PG8_MMA(ai, bj, At, Bt) do { __builtin_amdgcn_s_setprio(1); _Pragma("unroll") for (int m = 0; m < 4; ++m) _Pragma("unroll") for (int n = 0; n < 2; ++n) _Pragma("unroll") for (int k = 0; k < 2; ++k) \
;         acc[ai][bj][m][n] = __builtin_amdgcn_mfma_f32_16x16x32_bf16(Bt[n][k], At[m][k], acc[ai][bj][m][n], 0, 0, 0); __builtin_amdgcn_s_setprio(0); } while (0)
; #define PG8_WAIT_V(n) asm volatile("s_waitcnt vmcnt(" #n ")" ::: "memory")
; #define PG8_WAIT_L(n) asm volatile("s_waitcnt lgkmcnt(" #n ")" ::: "memory")
; #define PG8_BAR __builtin_amdgcn_s_barrier()
; #define PG8_SCHED __builtin_amdgcn_sched_barrier(0)
; template <class Epi, class Sched, bool ALIGN_EPI = false, bool SP2 = false>
; __device__ __forceinline__ void gemm_phase(PG8_LAS unsigned char* lds, const Gemm g, const Sched& S, const Epi& E) {
;     ...
;             PG8_WAIT_V(8); PG8_WAIT_L(0); PG8_BAR; PG8_MMA(1, 0, At, B0); PG8_MMA(1, 1, At, B1); PG8_BAR; PG8_SCHED;
;             PG8_LDB(B0, 1, 0); PG8_LDB(B1, 1, 1); PG8_SCHED; PG8_LDA(At, 1, 0); PG8_STAGE(PG8_SA(0, 1), a2 + hstep, voffA);
;             PG8_WAIT_V(8); PG8_WAIT_L(0); PG8_BAR; PG8_MMA(0, 0, At, B0); PG8_MMA(0, 1, At, B1); PG8_BAR; PG8_SCHED;
	v_mfma_f32_16x16x32_bf16 v[60:63], v[128:131], v[182:185], v[60:63]
	v_mfma_f32_16x16x32_bf16 v[56:59], v[136:139], v[182:185], v[56:59]
	v_mfma_f32_16x16x32_bf16 v[48:51], v[128:131], v[194:197], v[48:51]
	v_mfma_f32_16x16x32_bf16 v[40:43], v[136:139], v[194:197], v[40:43]
	v_mfma_f32_16x16x32_bf16 v[32:35], v[128:131], v[202:205], v[32:35]
	v_mfma_f32_16x16x32_bf16 v[24:27], v[136:139], v[202:205], v[24:27]
	v_mfma_f32_16x16x32_bf16 v[16:19], v[128:131], v[210:213], v[16:19]
	v_mfma_f32_16x16x32_bf16 v[8:11], v[136:139], v[210:213], v[8:11]
	v_mfma_f32_16x16x32_bf16 v[60:63], v[132:135], v[186:189], v[60:63]
	v_mfma_f32_16x16x32_bf16 v[56:59], v[140:143], v[186:189], v[56:59]
	v_mfma_f32_16x16x32_bf16 v[48:51], v[132:135], v[198:201], v[48:51]
	v_mfma_f32_16x16x32_bf16 v[40:43], v[140:143], v[198:201], v[40:43]
	v_mfma_f32_16x16x32_bf16 v[32:35], v[132:135], v[206:209], v[32:35]
	v_mfma_f32_16x16x32_bf16 v[24:27], v[140:143], v[206:209], v[24:27]
	v_mfma_f32_16x16x32_bf16 v[16:19], v[132:135], v[214:217], v[16:19]
	v_mfma_f32_16x16x32_bf16 v[8:11], v[140:143], v[214:217], v[8:11]
	v_mfma_f32_16x16x32_bf16 v[52:55], v[166:169], v[182:185], v[52:55]
	v_mfma_f32_16x16x32_bf16 v[44:47], v[174:177], v[182:185], v[44:47]
	v_mfma_f32_16x16x32_bf16 v[36:39], v[166:169], v[194:197], v[36:39]
	v_mfma_f32_16x16x32_bf16 v[28:31], v[174:177], v[194:197], v[28:31]
	v_mfma_f32_16x16x32_bf16 v[20:23], v[166:169], v[202:205], v[20:23]
	v_mfma_f32_16x16x32_bf16 v[12:15], v[174:177], v[202:205], v[12:15]
	v_mfma_f32_16x16x32_bf16 v[4:7], v[166:169], v[210:213], v[4:7]
	v_mfma_f32_16x16x32_bf16 v[0:3], v[174:177], v[210:213], v[0:3]
	v_mfma_f32_16x16x32_bf16 v[52:55], v[170:173], v[186:189], v[52:55]
	v_mfma_f32_16x16x32_bf16 v[44:47], v[178:181], v[186:189], v[44:47]
	v_mfma_f32_16x16x32_bf16 v[36:39], v[170:173], v[198:201], v[36:39]
	v_mfma_f32_16x16x32_bf16 v[28:31], v[178:181], v[198:201], v[28:31]
	v_mfma_f32_16x16x32_bf16 v[20:23], v[170:173], v[206:209], v[20:23]
	v_mfma_f32_16x16x32_bf16 v[12:15], v[178:181], v[206:209], v[12:15]
	v_mfma_f32_16x16x32_bf16 v[4:7], v[170:173], v[214:217], v[4:7]
	v_mfma_f32_16x16x32_bf16 v[0:3], v[178:181], v[214:217], v[0:3]
	s_barrier
	s_setprio 0
	s_add_i32 s10, 0, 0x18000
	s_add_i32 s11, 0, 0x1c000
	v_add_u32_e32 v140, s10, v163
	v_add_u32_e32 v162, s11, v163
	ds_read_b128 v[128:131], v140
	ds_read_b128 v[132:135], v140 offset:1024
	ds_read_b128 v[136:139], v140 offset:2048
	ds_read_b128 v[140:143], v140 offset:3072
	ds_read_b128 v[166:169], v162
	ds_read_b128 v[170:173], v162 offset:1024
	ds_read_b128 v[174:177], v162 offset:2048
	ds_read_b128 v[178:181], v162 offset:3072
	s_add_u32 s60, s60, 0x40000
	s_addc_u32 s61, s61, 0
	s_mov_b32 m0, s66
	v_lshl_add_u64 v[224:225], s[60:61], 0, v[144:145]
	ds_read_b128 v[182:185], v165 offset:32768
	ds_read_b128 v[186:189], v165 offset:33792
	ds_read_b128 v[194:197], v165 offset:34816
	ds_read_b128 v[198:201], v165 offset:35840
	ds_read_b128 v[202:205], v165 offset:36864
	ds_read_b128 v[206:209], v165 offset:37888
	ds_read_b128 v[210:213], v165 offset:38912
	ds_read_b128 v[214:217], v165 offset:39936
	global_load_lds_dwordx4 v[224:225], off
	v_lshl_add_u64 v[224:225], s[60:61], 0, v[148:149]
	s_mov_b32 m0, s67
	s_nop 0
	global_load_lds_dwordx4 v[224:225], off
	s_waitcnt vmcnt(8)
	s_waitcnt lgkmcnt(0)
	s_setprio 1
	s_barrier
	v_mfma_f32_16x16x32_bf16 v[124:127], v[128:131], v[182:185], v[124:127]
	v_mfma_f32_16x16x32_bf16 v[120:123], v[136:139], v[182:185], v[120:123]
	v_mfma_f32_16x16x32_bf16 v[112:115], v[128:131], v[194:197], v[112:115]
	v_mfma_f32_16x16x32_bf16 v[104:107], v[136:139], v[194:197], v[104:107]
	v_mfma_f32_16x16x32_bf16 v[96:99], v[128:131], v[202:205], v[96:99]
	v_mfma_f32_16x16x32_bf16 v[88:91], v[136:139], v[202:205], v[88:91]
	v_mfma_f32_16x16x32_bf16 v[80:83], v[128:131], v[210:213], v[80:83]
	v_mfma_f32_16x16x32_bf16 v[72:75], v[136:139], v[210:213], v[72:75]
	v_mfma_f32_16x16x32_bf16 v[124:127], v[132:135], v[186:189], v[124:127]
	v_mfma_f32_16x16x32_bf16 v[120:123], v[140:143], v[186:189], v[120:123]
	v_mfma_f32_16x16x32_bf16 v[112:115], v[132:135], v[198:201], v[112:115]
	v_mfma_f32_16x16x32_bf16 v[104:107], v[140:143], v[198:201], v[104:107]
	v_mfma_f32_16x16x32_bf16 v[96:99], v[132:135], v[206:209], v[96:99]
	v_mfma_f32_16x16x32_bf16 v[88:91], v[140:143], v[206:209], v[88:91]
	v_mfma_f32_16x16x32_bf16 v[80:83], v[132:135], v[214:217], v[80:83]
	v_mfma_f32_16x16x32_bf16 v[72:75], v[140:143], v[214:217], v[72:75]
	v_mfma_f32_16x16x32_bf16 v[116:119], v[166:169], v[182:185], v[116:119]
	v_mfma_f32_16x16x32_bf16 v[108:111], v[174:177], v[182:185], v[108:111]
	v_mfma_f32_16x16x32_bf16 v[100:103], v[166:169], v[194:197], v[100:103]
	v_mfma_f32_16x16x32_bf16 v[92:95], v[174:177], v[194:197], v[92:95]
	v_mfma_f32_16x16x32_bf16 v[84:87], v[166:169], v[202:205], v[84:87]
	v_mfma_f32_16x16x32_bf16 v[76:79], v[174:177], v[202:205], v[76:79]
	v_mfma_f32_16x16x32_bf16 v[68:71], v[166:169], v[210:213], v[68:71]
	v_mfma_f32_16x16x32_bf16 v[64:67], v[174:177], v[210:213], v[64:67]
	v_mfma_f32_16x16x32_bf16 v[116:119], v[170:173], v[186:189], v[116:119]
	v_mfma_f32_16x16x32_bf16 v[108:111], v[178:181], v[186:189], v[108:111]
	v_mfma_f32_16x16x32_bf16 v[100:103], v[170:173], v[198:201], v[100:103]
	v_mfma_f32_16x16x32_bf16 v[92:95], v[178:181], v[198:201], v[92:95]
	v_mfma_f32_16x16x32_bf16 v[84:87], v[170:173], v[206:209], v[84:87]
	v_mfma_f32_16x16x32_bf16 v[76:79], v[178:181], v[206:209], v[76:79]
	v_mfma_f32_16x16x32_bf16 v[68:71], v[170:173], v[214:217], v[68:71]
	v_mfma_f32_16x16x32_bf16 v[64:67], v[178:181], v[214:217], v[64:67]
	s_barrier
; #define PG8_STAGE(bufoff, gbase, voff) do { _Pragma("unroll") for (int _i = 0; _i < 2; ++_i) \
;         __builtin_amdgcn_global_load_lds((const unsigned*)((const char*)(gbase) + (voff)[_i]), (PG8_LAS unsigned*)(lds + (bufoff) + ldsw + _i * 8192), 16, 0, 0); } while (0)
; #define PG8_LDA(dst, b, h) do { _Pragma("unroll") for (int m = 0; m < 4; ++m) _Pragma("unroll") for (int k = 0; k < 2; ++k) dst[m][k] = *(const PG8_LAS bf16x8*)(lds + PG8_SA(b, h) + aoff + m * 2048 + k * 1024); } while (0)
; #define PG8_MMA(ai, bj, At, Bt) do { __builtin_amdgcn_s_setprio(1); _Pragma("unroll") for (int m = 0; m < 4; ++m) _Pragma("unroll") for (int n = 0; n < 2; ++n) _Pragma("unroll") for (int k = 0; k < 2; ++k) \
;         acc[ai][bj][m][n] = __builtin_amdgcn_mfma_f32_16x16x32_bf16(Bt[n][k], At[m][k], acc[ai][bj][m][n], 0, 0, 0); __builtin_amdgcn_s_setprio(0); } while (0)
; #define PG8_WAIT_V(n) asm volatile("s_waitcnt vmcnt(" #n ")" ::: "memory")
; #define PG8_WAIT_L(n) asm volatile("s_waitcnt lgkmcnt(" #n ")" ::: "memory")
; #define PG8_BAR __builtin_amdgcn_s_barrier()
; #define PG8_SCHED __builtin_amdgcn_sched_barrier(0)
; template <class Epi, class Sched, bool ALIGN_EPI = false, bool SP2 = false>
; __device__ __forceinline__ void gemm_phase(PG8_LAS unsigned char* lds, const Gemm g, const Sched& S, const Epi& E) {
;     ...
;         for (int t = 0; t < nt; t += 2) {
;             const bool last = (t == nt - 2);
;             const char* a1 = cA + (size_t)(t + 1) * kstep;
;             const char* a2 = last ? nA : cA + (size_t)(t + 2) * kstep; const char* b2 = last ? nB : cB + (size_t)(t + 2) * kstep;
;             const char* a3 = a2 + kstep; const char* b3 = b2 + kstep;
;     ...
;             PG8_LDA(At, 1, 1); PG8_STAGE(PG8_SB(1, 0), b3, voffB); PG8_STAGE(PG8_SB(1, 1), b3 + hstep, voffB); PG8_STAGE(PG8_SA(1, 0), a3, voffA);
;             PG8_WAIT_V(8); PG8_WAIT_L(0); PG8_BAR; PG8_MMA(1, 0, At, B0); PG8_MMA(1, 1, At, B1); PG8_BAR; PG8_SCHED;
	s_setprio 0
	s_add_i32 s10, s10, s63
	v_lshl_add_u64 v[190:191], v[190:191], 0, s[36:37]
	s_mov_b32 m0, s10
	ds_read_b128 v[182:185], v165 offset:49152
	ds_read_b128 v[186:189], v165 offset:50176
	ds_read_b128 v[194:197], v165 offset:51200
	ds_read_b128 v[198:201], v165 offset:52224
	ds_read_b128 v[202:205], v165 offset:53248
	ds_read_b128 v[206:209], v165 offset:54272
	ds_read_b128 v[210:213], v165 offset:55296
	ds_read_b128 v[214:217], v165 offset:56320
	global_load_lds_dwordx4 v[190:191], off
	s_add_i32 m0, s10, 0x2000
	s_add_u32 s58, s58, 0x40080
	v_lshl_add_u64 v[190:191], v[218:219], 0, s[36:37]
	s_addc_u32 s59, s59, 0
	s_add_i32 s10, s11, s63
	global_load_lds_dwordx4 v[190:191], off
	v_lshl_add_u64 v[190:191], s[58:59], 0, v[146:147]
	s_mov_b32 m0, s10
	s_nop 0
	global_load_lds_dwordx4 v[190:191], off
	v_lshl_add_u64 v[190:191], s[58:59], 0, v[150:151]
	s_add_i32 m0, s10, 0x2000
	s_nop 0
	global_load_lds_dwordx4 v[190:191], off
	v_lshl_add_u64 v[190:191], v[220:221], 0, s[36:37]
	s_mov_b32 m0, s70
	s_nop 0
	global_load_lds_dwordx4 v[190:191], off
	v_lshl_add_u64 v[190:191], v[222:223], 0, s[36:37]
	s_mov_b32 m0, s71
	s_nop 0
	global_load_lds_dwordx4 v[190:191], off
	s_waitcnt vmcnt(8)
	s_waitcnt lgkmcnt(0)
	s_setprio 1
	s_barrier
	v_mfma_f32_16x16x32_bf16 v[60:63], v[128:131], v[182:185], v[60:63]
	v_mfma_f32_16x16x32_bf16 v[56:59], v[136:139], v[182:185], v[56:59]
	v_mfma_f32_16x16x32_bf16 v[48:51], v[128:131], v[194:197], v[48:51]
	v_mfma_f32_16x16x32_bf16 v[40:43], v[136:139], v[194:197], v[40:43]
	v_mfma_f32_16x16x32_bf16 v[32:35], v[128:131], v[202:205], v[32:35]
	v_mfma_f32_16x16x32_bf16 v[24:27], v[136:139], v[202:205], v[24:27]
	v_mfma_f32_16x16x32_bf16 v[16:19], v[128:131], v[210:213], v[16:19]
	v_mfma_f32_16x16x32_bf16 v[8:11], v[136:139], v[210:213], v[8:11]
	v_mfma_f32_16x16x32_bf16 v[60:63], v[132:135], v[186:189], v[60:63]
	v_mfma_f32_16x16x32_bf16 v[56:59], v[140:143], v[186:189], v[56:59]
	v_mfma_f32_16x16x32_bf16 v[48:51], v[132:135], v[198:201], v[48:51]
	v_mfma_f32_16x16x32_bf16 v[40:43], v[140:143], v[198:201], v[40:43]
	v_mfma_f32_16x16x32_bf16 v[32:35], v[132:135], v[206:209], v[32:35]
	v_mfma_f32_16x16x32_bf16 v[24:27], v[140:143], v[206:209], v[24:27]
	v_mfma_f32_16x16x32_bf16 v[16:19], v[132:135], v[214:217], v[16:19]
	v_mfma_f32_16x16x32_bf16 v[8:11], v[140:143], v[214:217], v[8:11]
	v_mfma_f32_16x16x32_bf16 v[52:55], v[166:169], v[182:185], v[52:55]
	v_mfma_f32_16x16x32_bf16 v[44:47], v[174:177], v[182:185], v[44:47]
	v_mfma_f32_16x16x32_bf16 v[36:39], v[166:169], v[194:197], v[36:39]
	v_mfma_f32_16x16x32_bf16 v[28:31], v[174:177], v[194:197], v[28:31]
	v_mfma_f32_16x16x32_bf16 v[20:23], v[166:169], v[202:205], v[20:23]
	v_mfma_f32_16x16x32_bf16 v[12:15], v[174:177], v[202:205], v[12:15]
	v_mfma_f32_16x16x32_bf16 v[4:7], v[166:169], v[210:213], v[4:7]
	v_mfma_f32_16x16x32_bf16 v[0:3], v[174:177], v[210:213], v[0:3]
	v_mfma_f32_16x16x32_bf16 v[52:55], v[170:173], v[186:189], v[52:55]
	v_mfma_f32_16x16x32_bf16 v[44:47], v[178:181], v[186:189], v[44:47]
	v_mfma_f32_16x16x32_bf16 v[36:39], v[170:173], v[198:201], v[36:39]
	v_mfma_f32_16x16x32_bf16 v[28:31], v[178:181], v[198:201], v[28:31]
	v_mfma_f32_16x16x32_bf16 v[20:23], v[170:173], v[206:209], v[20:23]
	v_mfma_f32_16x16x32_bf16 v[12:15], v[178:181], v[206:209], v[12:15]
	v_mfma_f32_16x16x32_bf16 v[4:7], v[170:173], v[214:217], v[4:7]
	v_mfma_f32_16x16x32_bf16 v[0:3], v[178:181], v[214:217], v[0:3]
	s_cbranch_vccnz .Llast2_g2
	s_barrier
	s_setprio 0
	s_add_i32 s76, s76, 2
	s_add_u32 s56, s56, 0x100
	s_addc_u32 s57, s57, 0
	s_add_u32 s49, s49, 0x100
	s_addc_u32 s51, s51, 0
	s_cmp_gt_u32 s76, 13
	s_branch .LBB0_200

; #define PG8_STAGE(bufoff, gbase, voff) do { _Pragma("unroll") for (int _i = 0; _i < 2; ++_i) \
;         __builtin_amdgcn_global_load_lds((const unsigned*)((const char*)(gbase) + (voff)[_i]), (PG8_LAS unsigned*)(lds + (bufoff) + ldsw + _i * 8192), 16, 0, 0); } while (0)
; #define PG8_LDA(dst, b, h) do { _Pragma("unroll") for (int m = 0; m < 4; ++m) _Pragma("unroll") for (int k = 0; k < 2; ++k) dst[m][k] = *(const PG8_LAS bf16x8*)(lds + PG8_SA(b, h) + aoff + m * 2048 + k * 1024); } while (0)
; #define PG8_LDB(dst, b, h) do { _Pragma("unroll") for (int n = 0; n < 2; ++n) _Pragma("unroll") for (int k = 0; k < 2; ++k) dst[n][k] = *(const PG8_LAS bf16x8*)(lds + PG8_SB(b, h) + boff + n * 2048 + k * 1024); } while (0)
; #define PG8_MMA(ai, bj, At, Bt) do { __builtin_amdgcn_s_setprio(1); _Pragma("unroll") for (int m = 0; m < 4; ++m) _Pragma("unroll") for (int n = 0; n < 2; ++n) _Pragma("unroll") for (int k = 0; k < 2; ++k) \
;         acc[ai][bj][m][n] = __builtin_amdgcn_mfma_f32_16x16x32_bf16(Bt[n][k], At[m][k], acc[ai][bj][m][n], 0, 0, 0); __builtin_amdgcn_s_setprio(0); } while (0)
; #define PG8_WAIT_V(n) asm volatile("s_waitcnt vmcnt(" #n ")" ::: "memory")
; #define PG8_WAIT_L(n) asm volatile("s_waitcnt lgkmcnt(" #n ")" ::: "memory")
; #define PG8_BAR __builtin_amdgcn_s_barrier()
; #define PG8_SCHED __builtin_amdgcn_sched_barrier(0)
; template <class Epi, class Sched, bool ALIGN_EPI = false, bool SP2 = false>
; __device__ __forceinline__ void gemm_phase(PG8_LAS unsigned char* lds, const Gemm g, const Sched& S, const Epi& E) {
;     ...
;             PG8_LDB(B0, 0, 0); PG8_LDB(B1, 0, 1); PG8_SCHED; PG8_LDA(At, 0, 0); PG8_STAGE(PG8_SA(1, 1), a1 + hstep, voffA);
;             PG8_WAIT_V(8); PG8_WAIT_L(0); PG8_BAR; PG8_MMA(0, 0, At, B0); PG8_MMA(0, 1, At, B1); PG8_BAR; PG8_SCHED;
;             PG8_LDA(At, 0, 1); PG8_STAGE(PG8_SB(0, 0), b2, voffB); PG8_STAGE(PG8_SB(0, 1), b2 + hstep, voffB); PG8_STAGE(PG8_SA(0, 0), a2, voffA);
;             PG8_WAIT_V(8); PG8_WAIT_L(0); PG8_BAR; PG8_MMA(1, 0, At, B0); PG8_MMA(1, 1, At, B1); PG8_BAR; PG8_SCHED;
.LBB0_488:
	s_add_u32 s10, s34, 0xfffc0080
	s_addc_u32 s11, s35, -1
	s_add_i32 s77, 0, 0x10000
	s_cmp_eq_u32 s76, 4
	s_cselect_b64 vcc, -1, 0
	s_cselect_b32 s53, s45, s11
	s_cselect_b32 s52, s44, s10
	s_cselect_b32 s51, s49, s75
	s_cselect_b32 s50, s48, s19
	s_add_i32 s78, 0, 0x14000
	v_add_u32_e32 v140, s77, v246
	v_add_u32_e32 v156, s77, v246
	v_add_u32_e32 v156, 0x1000, v156
	ds_read_b128 v[128:131], v140
	ds_read_b128 v[132:135], v140 offset:1024
	ds_read_b128 v[136:139], v140 offset:2048
	ds_read_b128 v[140:143], v140 offset:3072
	ds_read_b128 v[144:147], v156
	ds_read_b128 v[148:151], v156 offset:1024
	ds_read_b128 v[152:155], v156 offset:2048
	ds_read_b128 v[156:159], v156 offset:3072
	v_lshl_add_u64 v[208:209], s[34:35], 0, v[204:205]
	s_add_i32 m0, s55, 0xc000
	ds_read_b128 v[160:163], v249
	ds_read_b128 v[164:167], v249 offset:1024
	ds_read_b128 v[168:171], v249 offset:2048
	ds_read_b128 v[172:175], v249 offset:3072
	ds_read_b128 v[176:179], v249 offset:4096
	ds_read_b128 v[180:183], v249 offset:5120
	ds_read_b128 v[184:187], v249 offset:6144
	ds_read_b128 v[188:191], v249 offset:7168
	global_load_lds_dwordx4 v[208:209], off
	v_lshl_add_u64 v[208:209], s[34:35], 0, v[206:207]
	s_add_i32 m0, s55, 0xe000
	s_nop 0
	global_load_lds_dwordx4 v[208:209], off
	s_waitcnt vmcnt(8)
	s_waitcnt lgkmcnt(0)
	s_setprio 1
	s_barrier
	v_mfma_f32_16x16x32_bf16 v[124:127], v[128:131], v[160:163], v[124:127]
	v_mfma_f32_16x16x32_bf16 v[120:123], v[136:139], v[160:163], v[120:123]
	v_mfma_f32_16x16x32_bf16 v[116:119], v[128:131], v[168:171], v[116:119]
	v_mfma_f32_16x16x32_bf16 v[112:115], v[136:139], v[168:171], v[112:115]
	v_mfma_f32_16x16x32_bf16 v[108:111], v[128:131], v[176:179], v[108:111]
	v_mfma_f32_16x16x32_bf16 v[104:107], v[136:139], v[176:179], v[104:107]
	v_mfma_f32_16x16x32_bf16 v[100:103], v[128:131], v[184:187], v[100:103]
	v_mfma_f32_16x16x32_bf16 v[96:99], v[136:139], v[184:187], v[96:99]
	v_mfma_f32_16x16x32_bf16 v[124:127], v[132:135], v[164:167], v[124:127]
	v_mfma_f32_16x16x32_bf16 v[120:123], v[140:143], v[164:167], v[120:123]
	v_mfma_f32_16x16x32_bf16 v[116:119], v[132:135], v[172:175], v[116:119]
	v_mfma_f32_16x16x32_bf16 v[112:115], v[140:143], v[172:175], v[112:115]
	v_mfma_f32_16x16x32_bf16 v[108:111], v[132:135], v[180:183], v[108:111]
	v_mfma_f32_16x16x32_bf16 v[104:107], v[140:143], v[180:183], v[104:107]
	v_mfma_f32_16x16x32_bf16 v[100:103], v[132:135], v[188:191], v[100:103]
	v_mfma_f32_16x16x32_bf16 v[96:99], v[140:143], v[188:191], v[96:99]
	v_mfma_f32_16x16x32_bf16 v[92:95], v[144:147], v[160:163], v[92:95]
	v_mfma_f32_16x16x32_bf16 v[88:91], v[152:155], v[160:163], v[88:91]
	v_mfma_f32_16x16x32_bf16 v[84:87], v[144:147], v[168:171], v[84:87]
	v_mfma_f32_16x16x32_bf16 v[80:83], v[152:155], v[168:171], v[80:83]
	v_mfma_f32_16x16x32_bf16 v[76:79], v[144:147], v[176:179], v[76:79]
	v_mfma_f32_16x16x32_bf16 v[72:75], v[152:155], v[176:179], v[72:75]
	v_mfma_f32_16x16x32_bf16 v[68:71], v[144:147], v[184:187], v[68:71]
	v_mfma_f32_16x16x32_bf16 v[64:67], v[152:155], v[184:187], v[64:67]
	v_mfma_f32_16x16x32_bf16 v[92:95], v[148:151], v[164:167], v[92:95]
	v_mfma_f32_16x16x32_bf16 v[88:91], v[156:159], v[164:167], v[88:91]
	v_mfma_f32_16x16x32_bf16 v[84:87], v[148:151], v[172:175], v[84:87]
	v_mfma_f32_16x16x32_bf16 v[80:83], v[156:159], v[172:175], v[80:83]
	v_mfma_f32_16x16x32_bf16 v[76:79], v[148:151], v[180:183], v[76:79]
	v_mfma_f32_16x16x32_bf16 v[72:75], v[156:159], v[180:183], v[72:75]
	v_mfma_f32_16x16x32_bf16 v[68:71], v[148:151], v[188:191], v[68:71]
	v_mfma_f32_16x16x32_bf16 v[64:67], v[156:159], v[188:191], v[64:67]
	s_barrier
	s_setprio 0
	s_add_i32 s10, s77, s14
	v_lshl_add_u64 v[208:209], s[50:51], 0, v[198:199]
	s_mov_b32 m0, s10
	ds_read_b128 v[160:163], v249 offset:16384
	ds_read_b128 v[164:167], v249 offset:17408
	ds_read_b128 v[168:171], v249 offset:18432
	ds_read_b128 v[172:175], v249 offset:19456
	ds_read_b128 v[176:179], v249 offset:20480
	ds_read_b128 v[180:183], v249 offset:21504
	ds_read_b128 v[184:187], v249 offset:22528
	ds_read_b128 v[188:191], v249 offset:23552
	global_load_lds_dwordx4 v[208:209], off
	s_add_i32 m0, s10, 0x2000
	s_add_u32 s10, s50, 0x40000
	v_lshl_add_u64 v[210:211], s[50:51], 0, v[194:195]
	s_addc_u32 s11, s51, 0
	s_add_i32 s77, s78, s14
	global_load_lds_dwordx4 v[210:211], off
	v_lshl_add_u64 v[212:213], s[10:11], 0, v[198:199]
	s_mov_b32 m0, s77
	v_lshl_add_u64 v[214:215], s[52:53], 0, v[196:197]
	global_load_lds_dwordx4 v[212:213], off
	v_lshl_add_u64 v[212:213], s[10:11], 0, v[194:195]
	s_add_i32 m0, s77, 0x2000
	s_nop 0
	global_load_lds_dwordx4 v[212:213], off
	v_lshl_add_u64 v[212:213], s[52:53], 0, v[200:201]
	s_mov_b32 m0, s55
	s_nop 0
	global_load_lds_dwordx4 v[212:213], off
	s_mov_b32 m0, s58
	s_nop 0
	global_load_lds_dwordx4 v[214:215], off
	s_waitcnt vmcnt(8)
	s_waitcnt lgkmcnt(0)
	s_setprio 1
	s_barrier
; #define PG8_STAGE(bufoff, gbase, voff) do { _Pragma("unroll") for (int _i = 0; _i < 2; ++_i) \
;         __builtin_amdgcn_global_load_lds((const unsigned*)((const char*)(gbase) + (voff)[_i]), (PG8_LAS unsigned*)(lds + (bufoff) + ldsw + _i * 8192), 16, 0, 0); } while (0)
; #define PG8_LDA(dst, b, h) do { _Pragma("unroll") for (int m = 0; m < 4; ++m) _Pragma("unroll") for (int k = 0; k < 2; ++k) dst[m][k] = *(const PG8_LAS bf16x8*)(lds + PG8_SA(b, h) + aoff + m * 2048 + k * 1024); } while (0)
; #define PG8_LDB(dst, b, h) do { _Pragma("unroll") for (int n = 0; n < 2; ++n) _Pragma("unroll") for (int k = 0; k < 2; ++k) dst[n][k] = *(const PG8_LAS bf16x8*)(lds + PG8_SB(b, h) + boff + n * 2048 + k * 1024); } while (0)
; #define PG8_MMA(ai, bj, At, Bt) do { __builtin_amdgcn_s_setprio(1); _Pragma("unroll") for (int m = 0; m < 4; ++m) _Pragma("unroll") for (int n = 0; n < 2; ++n) _Pragma("unroll") for (int k = 0; k < 2; ++k) \
;         acc[ai][bj][m][n] = __builtin_amdgcn_mfma_f32_16x16x32_bf16(Bt[n][k], At[m][k], acc[ai][bj][m][n], 0, 0, 0); __builtin_amdgcn_s_setprio(0); } while (0)
; #define PG8_WAIT_V(n) asm volatile("s_waitcnt vmcnt(" #n ")" ::: "memory")
; #define PG8_WAIT_L(n) asm volatile("s_waitcnt lgkmcnt(" #n ")" ::: "memory")
; #define PG8_BAR __builtin_amdgcn_s_barrier()
; #define PG8_SCHED __builtin_amdgcn_sched_barrier(0)
; template <class Epi, class Sched, bool ALIGN_EPI = false, bool SP2 = false>
; __device__ __forceinline__ void gemm_phase(PG8_LAS unsigned char* lds, const Gemm g, const Sched& S, const Epi& E) {
;     ...
;             PG8_WAIT_V(8); PG8_WAIT_L(0); PG8_BAR; PG8_MMA(1, 0, At, B0); PG8_MMA(1, 1, At, B1); PG8_BAR; PG8_SCHED;
;             PG8_LDB(B0, 1, 0); PG8_LDB(B1, 1, 1); PG8_SCHED; PG8_LDA(At, 1, 0); PG8_STAGE(PG8_SA(0, 1), a2 + hstep, voffA);
;             PG8_WAIT_V(8); PG8_WAIT_L(0); PG8_BAR; PG8_MMA(0, 0, At, B0); PG8_MMA(0, 1, At, B1); PG8_BAR; PG8_SCHED;
	v_mfma_f32_16x16x32_bf16 v[60:63], v[128:131], v[160:163], v[60:63]
	v_mfma_f32_16x16x32_bf16 v[56:59], v[136:139], v[160:163], v[56:59]
	v_mfma_f32_16x16x32_bf16 v[52:55], v[128:131], v[168:171], v[52:55]
	v_mfma_f32_16x16x32_bf16 v[48:51], v[136:139], v[168:171], v[48:51]
	v_mfma_f32_16x16x32_bf16 v[44:47], v[128:131], v[176:179], v[44:47]
	v_mfma_f32_16x16x32_bf16 v[40:43], v[136:139], v[176:179], v[40:43]
	v_mfma_f32_16x16x32_bf16 v[36:39], v[128:131], v[184:187], v[36:39]
	v_mfma_f32_16x16x32_bf16 v[32:35], v[136:139], v[184:187], v[32:35]
	v_mfma_f32_16x16x32_bf16 v[60:63], v[132:135], v[164:167], v[60:63]
	v_mfma_f32_16x16x32_bf16 v[56:59], v[140:143], v[164:167], v[56:59]
	v_mfma_f32_16x16x32_bf16 v[52:55], v[132:135], v[172:175], v[52:55]
	v_mfma_f32_16x16x32_bf16 v[48:51], v[140:143], v[172:175], v[48:51]
	v_mfma_f32_16x16x32_bf16 v[44:47], v[132:135], v[180:183], v[44:47]
	v_mfma_f32_16x16x32_bf16 v[40:43], v[140:143], v[180:183], v[40:43]
	v_mfma_f32_16x16x32_bf16 v[36:39], v[132:135], v[188:191], v[36:39]
	v_mfma_f32_16x16x32_bf16 v[32:35], v[140:143], v[188:191], v[32:35]
	v_mfma_f32_16x16x32_bf16 v[28:31], v[144:147], v[160:163], v[28:31]
	v_mfma_f32_16x16x32_bf16 v[24:27], v[152:155], v[160:163], v[24:27]
	v_mfma_f32_16x16x32_bf16 v[20:23], v[144:147], v[168:171], v[20:23]
	v_mfma_f32_16x16x32_bf16 v[16:19], v[152:155], v[168:171], v[16:19]
	v_mfma_f32_16x16x32_bf16 v[12:15], v[144:147], v[176:179], v[12:15]
	v_mfma_f32_16x16x32_bf16 v[8:11], v[152:155], v[176:179], v[8:11]
	v_mfma_f32_16x16x32_bf16 v[4:7], v[144:147], v[184:187], v[4:7]
	v_mfma_f32_16x16x32_bf16 v[0:3], v[152:155], v[184:187], v[0:3]
	v_mfma_f32_16x16x32_bf16 v[28:31], v[148:151], v[164:167], v[28:31]
	v_mfma_f32_16x16x32_bf16 v[24:27], v[156:159], v[164:167], v[24:27]
	v_mfma_f32_16x16x32_bf16 v[20:23], v[148:151], v[172:175], v[20:23]
	v_mfma_f32_16x16x32_bf16 v[16:19], v[156:159], v[172:175], v[16:19]
	v_mfma_f32_16x16x32_bf16 v[12:15], v[148:151], v[180:183], v[12:15]
	v_mfma_f32_16x16x32_bf16 v[8:11], v[156:159], v[180:183], v[8:11]
	v_mfma_f32_16x16x32_bf16 v[4:7], v[148:151], v[188:191], v[4:7]
	v_mfma_f32_16x16x32_bf16 v[0:3], v[156:159], v[188:191], v[0:3]
	s_barrier
	s_setprio 0
	s_add_i32 s77, 0, 0x18000
	s_add_i32 s78, 0, 0x1c000
	v_add_u32_e32 v140, s77, v246
	v_add_u32_e32 v156, s77, v246
	v_add_u32_e32 v156, 0x1000, v156
	ds_read_b128 v[128:131], v140
	ds_read_b128 v[132:135], v140 offset:1024
	ds_read_b128 v[136:139], v140 offset:2048
	ds_read_b128 v[140:143], v140 offset:3072
	ds_read_b128 v[144:147], v156
	ds_read_b128 v[148:151], v156 offset:1024
	ds_read_b128 v[152:155], v156 offset:2048
	ds_read_b128 v[156:159], v156 offset:3072
	s_add_u32 s10, s52, 0x40000
	s_addc_u32 s11, s53, 0
	s_mov_b32 m0, s59
	v_lshl_add_u64 v[216:217], s[10:11], 0, v[200:201]
	ds_read_b128 v[160:163], v249 offset:32768
	ds_read_b128 v[164:167], v249 offset:33792
	ds_read_b128 v[168:171], v249 offset:34816
	ds_read_b128 v[172:175], v249 offset:35840
	ds_read_b128 v[176:179], v249 offset:36864
	ds_read_b128 v[180:183], v249 offset:37888
	ds_read_b128 v[184:187], v249 offset:38912
	ds_read_b128 v[188:191], v249 offset:39936
	global_load_lds_dwordx4 v[216:217], off
	v_lshl_add_u64 v[216:217], s[10:11], 0, v[196:197]
	s_mov_b32 m0, s60
	s_nop 0
	global_load_lds_dwordx4 v[216:217], off
	s_waitcnt vmcnt(8)
	s_waitcnt lgkmcnt(0)
	s_setprio 1
	s_barrier
	v_mfma_f32_16x16x32_bf16 v[124:127], v[128:131], v[160:163], v[124:127]
	v_mfma_f32_16x16x32_bf16 v[120:123], v[136:139], v[160:163], v[120:123]
	v_mfma_f32_16x16x32_bf16 v[116:119], v[128:131], v[168:171], v[116:119]
	v_mfma_f32_16x16x32_bf16 v[112:115], v[136:139], v[168:171], v[112:115]
	v_mfma_f32_16x16x32_bf16 v[108:111], v[128:131], v[176:179], v[108:111]
	v_mfma_f32_16x16x32_bf16 v[104:107], v[136:139], v[176:179], v[104:107]
	v_mfma_f32_16x16x32_bf16 v[100:103], v[128:131], v[184:187], v[100:103]
	v_mfma_f32_16x16x32_bf16 v[96:99], v[136:139], v[184:187], v[96:99]
	v_mfma_f32_16x16x32_bf16 v[124:127], v[132:135], v[164:167], v[124:127]
	v_mfma_f32_16x16x32_bf16 v[120:123], v[140:143], v[164:167], v[120:123]
	v_mfma_f32_16x16x32_bf16 v[116:119], v[132:135], v[172:175], v[116:119]
	v_mfma_f32_16x16x32_bf16 v[112:115], v[140:143], v[172:175], v[112:115]
	v_mfma_f32_16x16x32_bf16 v[108:111], v[132:135], v[180:183], v[108:111]
	v_mfma_f32_16x16x32_bf16 v[104:107], v[140:143], v[180:183], v[104:107]
	v_mfma_f32_16x16x32_bf16 v[100:103], v[132:135], v[188:191], v[100:103]
	v_mfma_f32_16x16x32_bf16 v[96:99], v[140:143], v[188:191], v[96:99]
	v_mfma_f32_16x16x32_bf16 v[92:95], v[144:147], v[160:163], v[92:95]
	v_mfma_f32_16x16x32_bf16 v[88:91], v[152:155], v[160:163], v[88:91]
	v_mfma_f32_16x16x32_bf16 v[84:87], v[144:147], v[168:171], v[84:87]
	v_mfma_f32_16x16x32_bf16 v[80:83], v[152:155], v[168:171], v[80:83]
	v_mfma_f32_16x16x32_bf16 v[76:79], v[144:147], v[176:179], v[76:79]
	v_mfma_f32_16x16x32_bf16 v[72:75], v[152:155], v[176:179], v[72:75]
	v_mfma_f32_16x16x32_bf16 v[68:71], v[144:147], v[184:187], v[68:71]
	v_mfma_f32_16x16x32_bf16 v[64:67], v[152:155], v[184:187], v[64:67]
	v_mfma_f32_16x16x32_bf16 v[92:95], v[148:151], v[164:167], v[92:95]
	v_mfma_f32_16x16x32_bf16 v[88:91], v[156:159], v[164:167], v[88:91]
	v_mfma_f32_16x16x32_bf16 v[84:87], v[148:151], v[172:175], v[84:87]
	v_mfma_f32_16x16x32_bf16 v[80:83], v[156:159], v[172:175], v[80:83]
	v_mfma_f32_16x16x32_bf16 v[76:79], v[148:151], v[180:183], v[76:79]
	v_mfma_f32_16x16x32_bf16 v[72:75], v[156:159], v[180:183], v[72:75]
	v_mfma_f32_16x16x32_bf16 v[68:71], v[148:151], v[188:191], v[68:71]
	v_mfma_f32_16x16x32_bf16 v[64:67], v[156:159], v[188:191], v[64:67]
	s_barrier
; #define PG8_STAGE(bufoff, gbase, voff) do { _Pragma("unroll") for (int _i = 0; _i < 2; ++_i) \
;         __builtin_amdgcn_global_load_lds((const unsigned*)((const char*)(gbase) + (voff)[_i]), (PG8_LAS unsigned*)(lds + (bufoff) + ldsw + _i * 8192), 16, 0, 0); } while (0)
; #define PG8_LDA(dst, b, h) do { _Pragma("unroll") for (int m = 0; m < 4; ++m) _Pragma("unroll") for (int k = 0; k < 2; ++k) dst[m][k] = *(const PG8_LAS bf16x8*)(lds + PG8_SA(b, h) + aoff + m * 2048 + k * 1024); } while (0)
; #define PG8_MMA(ai, bj, At, Bt) do { __builtin_amdgcn_s_setprio(1); _Pragma("unroll") for (int m = 0; m < 4; ++m) _Pragma("unroll") for (int n = 0; n < 2; ++n) _Pragma("unroll") for (int k = 0; k < 2; ++k) \
;         acc[ai][bj][m][n] = __builtin_amdgcn_mfma_f32_16x16x32_bf16(Bt[n][k], At[m][k], acc[ai][bj][m][n], 0, 0, 0); __builtin_amdgcn_s_setprio(0); } while (0)
; #define PG8_WAIT_V(n) asm volatile("s_waitcnt vmcnt(" #n ")" ::: "memory")
; #define PG8_WAIT_L(n) asm volatile("s_waitcnt lgkmcnt(" #n ")" ::: "memory")
; #define PG8_BAR __builtin_amdgcn_s_barrier()
; #define PG8_SCHED __builtin_amdgcn_sched_barrier(0)
; template <class Epi, class Sched, bool ALIGN_EPI = false, bool SP2 = false>
; __device__ __forceinline__ void gemm_phase(PG8_LAS unsigned char* lds, const Gemm g, const Sched& S, const Epi& E) {
;     ...
;         for (int t = 0; t < nt; t += 2) {
;             const bool last = (t == nt - 2);
;             const char* a1 = cA + (size_t)(t + 1) * kstep;
;             const char* a2 = last ? nA : cA + (size_t)(t + 2) * kstep; const char* b2 = last ? nB : cB + (size_t)(t + 2) * kstep;
;             const char* a3 = a2 + kstep; const char* b3 = b2 + kstep;
;     ...
;             PG8_LDA(At, 1, 1); PG8_STAGE(PG8_SB(1, 0), b3, voffB); PG8_STAGE(PG8_SB(1, 1), b3 + hstep, voffB); PG8_STAGE(PG8_SA(1, 0), a3, voffA);
;             PG8_WAIT_V(8); PG8_WAIT_L(0); PG8_BAR; PG8_MMA(1, 0, At, B0); PG8_MMA(1, 1, At, B1); PG8_BAR; PG8_SCHED;
	s_setprio 0
	s_add_i32 s10, s77, s14
	v_lshl_add_u64 v[208:209], v[208:209], 0, s[36:37]
	s_mov_b32 m0, s10
	ds_read_b128 v[160:163], v249 offset:49152
	ds_read_b128 v[164:167], v249 offset:50176
	ds_read_b128 v[168:171], v249 offset:51200
	ds_read_b128 v[172:175], v249 offset:52224
	ds_read_b128 v[176:179], v249 offset:53248
	ds_read_b128 v[180:183], v249 offset:54272
	ds_read_b128 v[184:187], v249 offset:55296
	ds_read_b128 v[188:191], v249 offset:56320
	global_load_lds_dwordx4 v[208:209], off
	s_add_i32 m0, s10, 0x2000
	s_add_u32 s10, s50, 0x40080
	v_lshl_add_u64 v[208:209], v[210:211], 0, s[36:37]
	s_addc_u32 s11, s51, 0
	s_add_i32 s50, s78, s14
	global_load_lds_dwordx4 v[208:209], off
	v_lshl_add_u64 v[208:209], s[10:11], 0, v[198:199]
	s_mov_b32 m0, s50
	s_nop 0
	global_load_lds_dwordx4 v[208:209], off
	v_lshl_add_u64 v[208:209], s[10:11], 0, v[194:195]
	s_add_i32 m0, s50, 0x2000
	s_nop 0
	global_load_lds_dwordx4 v[208:209], off
	v_lshl_add_u64 v[208:209], v[212:213], 0, s[36:37]
	s_mov_b32 m0, s65
	s_nop 0
	global_load_lds_dwordx4 v[208:209], off
	v_lshl_add_u64 v[208:209], v[214:215], 0, s[36:37]
	s_mov_b32 m0, s66
	s_nop 0
	global_load_lds_dwordx4 v[208:209], off
	s_waitcnt vmcnt(8)
	s_waitcnt lgkmcnt(0)
	s_setprio 1
	s_barrier
	v_mfma_f32_16x16x32_bf16 v[60:63], v[128:131], v[160:163], v[60:63]
	v_mfma_f32_16x16x32_bf16 v[56:59], v[136:139], v[160:163], v[56:59]
	v_mfma_f32_16x16x32_bf16 v[52:55], v[128:131], v[168:171], v[52:55]
	v_mfma_f32_16x16x32_bf16 v[48:51], v[136:139], v[168:171], v[48:51]
	v_mfma_f32_16x16x32_bf16 v[44:47], v[128:131], v[176:179], v[44:47]
	v_mfma_f32_16x16x32_bf16 v[40:43], v[136:139], v[176:179], v[40:43]
	v_mfma_f32_16x16x32_bf16 v[36:39], v[128:131], v[184:187], v[36:39]
	v_mfma_f32_16x16x32_bf16 v[32:35], v[136:139], v[184:187], v[32:35]
	v_mfma_f32_16x16x32_bf16 v[60:63], v[132:135], v[164:167], v[60:63]
	v_mfma_f32_16x16x32_bf16 v[56:59], v[140:143], v[164:167], v[56:59]
	v_mfma_f32_16x16x32_bf16 v[52:55], v[132:135], v[172:175], v[52:55]
	v_mfma_f32_16x16x32_bf16 v[48:51], v[140:143], v[172:175], v[48:51]
	v_mfma_f32_16x16x32_bf16 v[44:47], v[132:135], v[180:183], v[44:47]
	v_mfma_f32_16x16x32_bf16 v[40:43], v[140:143], v[180:183], v[40:43]
	v_mfma_f32_16x16x32_bf16 v[36:39], v[132:135], v[188:191], v[36:39]
	v_mfma_f32_16x16x32_bf16 v[32:35], v[140:143], v[188:191], v[32:35]
	v_mfma_f32_16x16x32_bf16 v[28:31], v[144:147], v[160:163], v[28:31]
	v_mfma_f32_16x16x32_bf16 v[24:27], v[152:155], v[160:163], v[24:27]
	v_mfma_f32_16x16x32_bf16 v[20:23], v[144:147], v[168:171], v[20:23]
	v_mfma_f32_16x16x32_bf16 v[16:19], v[152:155], v[168:171], v[16:19]
	v_mfma_f32_16x16x32_bf16 v[12:15], v[144:147], v[176:179], v[12:15]
	v_mfma_f32_16x16x32_bf16 v[8:11], v[152:155], v[176:179], v[8:11]
	v_mfma_f32_16x16x32_bf16 v[4:7], v[144:147], v[184:187], v[4:7]
	v_mfma_f32_16x16x32_bf16 v[0:3], v[152:155], v[184:187], v[0:3]
	v_mfma_f32_16x16x32_bf16 v[28:31], v[148:151], v[164:167], v[28:31]
	v_mfma_f32_16x16x32_bf16 v[24:27], v[156:159], v[164:167], v[24:27]
	v_mfma_f32_16x16x32_bf16 v[20:23], v[148:151], v[172:175], v[20:23]
	v_mfma_f32_16x16x32_bf16 v[16:19], v[156:159], v[172:175], v[16:19]
	v_mfma_f32_16x16x32_bf16 v[12:15], v[148:151], v[180:183], v[12:15]
	v_mfma_f32_16x16x32_bf16 v[8:11], v[156:159], v[180:183], v[8:11]
	v_mfma_f32_16x16x32_bf16 v[4:7], v[148:151], v[188:191], v[4:7]
	v_mfma_f32_16x16x32_bf16 v[0:3], v[156:159], v[188:191], v[0:3]
	s_cbranch_vccnz .Llast2_g3
	s_barrier
	s_setprio 0
	s_add_i32 s76, s76, 2
	s_add_u32 s34, s34, 0x100
	s_addc_u32 s35, s35, 0
	s_add_u32 s19, s19, 0x100
	s_addc_u32 s75, s75, 0
	s_cmp_gt_u32 s76, 5
	s_branch .LBB0_488

; #define PG8_STAGE(bufoff, gbase, voff) do { _Pragma("unroll") for (int _i = 0; _i < 2; ++_i) \
;         __builtin_amdgcn_global_load_lds((const unsigned*)((const char*)(gbase) + (voff)[_i]), (PG8_LAS unsigned*)(lds + (bufoff) + ldsw + _i * 8192), 16, 0, 0); } while (0)
; #define PG8_LDA(dst, b, h) do { _Pragma("unroll") for (int m = 0; m < 4; ++m) _Pragma("unroll") for (int k = 0; k < 2; ++k) dst[m][k] = *(const PG8_LAS bf16x8*)(lds + PG8_SA(b, h) + aoff + m * 2048 + k * 1024); } while (0)
; #define PG8_LDB(dst, b, h) do { _Pragma("unroll") for (int n = 0; n < 2; ++n) _Pragma("unroll") for (int k = 0; k < 2; ++k) dst[n][k] = *(const PG8_LAS bf16x8*)(lds + PG8_SB(b, h) + boff + n * 2048 + k * 1024); } while (0)
; #define PG8_MMA(ai, bj, At, Bt) do { __builtin_amdgcn_s_setprio(1); _Pragma("unroll") for (int m = 0; m < 4; ++m) _Pragma("unroll") for (int n = 0; n < 2; ++n) _Pragma("unroll") for (int k = 0; k < 2; ++k) \
;         acc[ai][bj][m][n] = __builtin_amdgcn_mfma_f32_16x16x32_bf16(Bt[n][k], At[m][k], acc[ai][bj][m][n], 0, 0, 0); __builtin_amdgcn_s_setprio(0); } while (0)
; #define PG8_WAIT_V(n) asm volatile("s_waitcnt vmcnt(" #n ")" ::: "memory")
; #define PG8_WAIT_L(n) asm volatile("s_waitcnt lgkmcnt(" #n ")" ::: "memory")
; #define PG8_BAR __builtin_amdgcn_s_barrier()
; #define PG8_SCHED __builtin_amdgcn_sched_barrier(0)
; template <class Epi, class Sched, bool ALIGN_EPI = false, bool SP2 = false>
; __device__ __forceinline__ void gemm_phase(PG8_LAS unsigned char* lds, const Gemm g, const Sched& S, const Epi& E) {
;     ...
;             PG8_LDB(B0, 0, 0); PG8_LDB(B1, 0, 1); PG8_SCHED; PG8_LDA(At, 0, 0); PG8_STAGE(PG8_SA(1, 1), a1 + hstep, voffA);
;             PG8_WAIT_V(8); PG8_WAIT_L(0); PG8_BAR; PG8_MMA(0, 0, At, B0); PG8_MMA(0, 1, At, B1); PG8_BAR; PG8_SCHED;
;             PG8_LDA(At, 0, 1); PG8_STAGE(PG8_SB(0, 0), b2, voffB); PG8_STAGE(PG8_SB(0, 1), b2 + hstep, voffB); PG8_STAGE(PG8_SA(0, 0), a2, voffA);
;             PG8_WAIT_V(8); PG8_WAIT_L(0); PG8_BAR; PG8_MMA(1, 0, At, B0); PG8_MMA(1, 1, At, B1); PG8_BAR; PG8_SCHED;
.LBB0_577:
	s_add_u32 s10, s44, 0xfffc0080
	s_addc_u32 s11, s45, -1
	s_add_i32 s64, 0, 0x10000
	s_cmp_eq_u32 s63, 12
	s_cselect_b64 vcc, -1, 0
	s_cselect_b32 s49, s29, s11
	s_cselect_b32 s48, s43, s10
	v_add_u32_e32 v146, s64, v149
	s_cselect_b32 s47, s27, s62
	s_cselect_b32 s46, s60, s61
	s_add_i32 s65, 0, 0x14000
	ds_read_b128 v[128:131], v146
	ds_read_b128 v[154:157], v146 offset:1024
	ds_read_b128 v[158:161], v146 offset:2048
	ds_read_b128 v[162:165], v146 offset:3072
	v_add_u32_e32 v146, s65, v149
	ds_read_b128 v[166:169], v146
	ds_read_b128 v[170:173], v146 offset:1024
	ds_read_b128 v[174:177], v146 offset:2048
	ds_read_b128 v[178:181], v146 offset:3072
	v_lshl_add_u64 v[190:191], s[44:45], 0, v[142:143]
	s_add_i32 m0, s51, 0xc000
	ds_read_b128 v[182:185], v153
	ds_read_b128 v[186:189], v153 offset:1024
	ds_read_b128 v[194:197], v153 offset:2048
	ds_read_b128 v[198:201], v153 offset:3072
	ds_read_b128 v[202:205], v153 offset:4096
	ds_read_b128 v[206:209], v153 offset:5120
	ds_read_b128 v[210:213], v153 offset:6144
	ds_read_b128 v[214:217], v153 offset:7168
	global_load_lds_dwordx4 v[190:191], off
	v_lshl_add_u64 v[190:191], s[44:45], 0, v[144:145]
	s_add_i32 m0, s51, 0xe000
	s_nop 0
	global_load_lds_dwordx4 v[190:191], off
	s_waitcnt vmcnt(8)
	s_waitcnt lgkmcnt(0)
	s_setprio 1
	s_barrier
	v_mfma_f32_16x16x32_bf16 v[124:127], v[128:131], v[182:185], v[124:127]
	v_mfma_f32_16x16x32_bf16 v[116:119], v[158:161], v[182:185], v[116:119]
	v_mfma_f32_16x16x32_bf16 v[108:111], v[128:131], v[194:197], v[108:111]
	v_mfma_f32_16x16x32_bf16 v[100:103], v[158:161], v[194:197], v[100:103]
	v_mfma_f32_16x16x32_bf16 v[92:95], v[128:131], v[202:205], v[92:95]
	v_mfma_f32_16x16x32_bf16 v[84:87], v[158:161], v[202:205], v[84:87]
	v_mfma_f32_16x16x32_bf16 v[76:79], v[128:131], v[210:213], v[76:79]
	v_mfma_f32_16x16x32_bf16 v[68:71], v[158:161], v[210:213], v[68:71]
	v_mfma_f32_16x16x32_bf16 v[124:127], v[154:157], v[186:189], v[124:127]
	v_mfma_f32_16x16x32_bf16 v[116:119], v[162:165], v[186:189], v[116:119]
	v_mfma_f32_16x16x32_bf16 v[108:111], v[154:157], v[198:201], v[108:111]
	v_mfma_f32_16x16x32_bf16 v[100:103], v[162:165], v[198:201], v[100:103]
	v_mfma_f32_16x16x32_bf16 v[92:95], v[154:157], v[206:209], v[92:95]
	v_mfma_f32_16x16x32_bf16 v[84:87], v[162:165], v[206:209], v[84:87]
	v_mfma_f32_16x16x32_bf16 v[76:79], v[154:157], v[214:217], v[76:79]
	v_mfma_f32_16x16x32_bf16 v[68:71], v[162:165], v[214:217], v[68:71]
	v_mfma_f32_16x16x32_bf16 v[120:123], v[166:169], v[182:185], v[120:123]
	v_mfma_f32_16x16x32_bf16 v[112:115], v[174:177], v[182:185], v[112:115]
	v_mfma_f32_16x16x32_bf16 v[104:107], v[166:169], v[194:197], v[104:107]
	v_mfma_f32_16x16x32_bf16 v[96:99], v[174:177], v[194:197], v[96:99]
	v_mfma_f32_16x16x32_bf16 v[88:91], v[166:169], v[202:205], v[88:91]
	v_mfma_f32_16x16x32_bf16 v[80:83], v[174:177], v[202:205], v[80:83]
	v_mfma_f32_16x16x32_bf16 v[72:75], v[166:169], v[210:213], v[72:75]
	v_mfma_f32_16x16x32_bf16 v[64:67], v[174:177], v[210:213], v[64:67]
	v_mfma_f32_16x16x32_bf16 v[120:123], v[170:173], v[186:189], v[120:123]
	v_mfma_f32_16x16x32_bf16 v[112:115], v[178:181], v[186:189], v[112:115]
	v_mfma_f32_16x16x32_bf16 v[104:107], v[170:173], v[198:201], v[104:107]
	v_mfma_f32_16x16x32_bf16 v[96:99], v[178:181], v[198:201], v[96:99]
	v_mfma_f32_16x16x32_bf16 v[88:91], v[170:173], v[206:209], v[88:91]
	v_mfma_f32_16x16x32_bf16 v[80:83], v[178:181], v[206:209], v[80:83]
	v_mfma_f32_16x16x32_bf16 v[72:75], v[170:173], v[214:217], v[72:75]
	v_mfma_f32_16x16x32_bf16 v[64:67], v[178:181], v[214:217], v[64:67]
	s_barrier
	s_setprio 0
	s_add_i32 s10, s64, s19
	v_lshl_add_u64 v[190:191], s[46:47], 0, v[136:137]
	s_mov_b32 m0, s10
	ds_read_b128 v[182:185], v153 offset:16384
	ds_read_b128 v[186:189], v153 offset:17408
	ds_read_b128 v[194:197], v153 offset:18432
	ds_read_b128 v[198:201], v153 offset:19456
	ds_read_b128 v[202:205], v153 offset:20480
	ds_read_b128 v[206:209], v153 offset:21504
	ds_read_b128 v[210:213], v153 offset:22528
	ds_read_b128 v[214:217], v153 offset:23552
	global_load_lds_dwordx4 v[190:191], off
	s_add_i32 m0, s10, 0x2000
	s_add_u32 s10, s46, 0x40000
	v_lshl_add_u64 v[218:219], s[46:47], 0, v[132:133]
	s_addc_u32 s11, s47, 0
	s_add_i32 s64, s65, s19
	global_load_lds_dwordx4 v[218:219], off
	v_lshl_add_u64 v[220:221], s[10:11], 0, v[136:137]
	s_mov_b32 m0, s64
	v_lshl_add_u64 v[222:223], s[48:49], 0, v[134:135]
	global_load_lds_dwordx4 v[220:221], off
	v_lshl_add_u64 v[220:221], s[10:11], 0, v[132:133]
	s_add_i32 m0, s64, 0x2000
	s_nop 0
	global_load_lds_dwordx4 v[220:221], off
	v_lshl_add_u64 v[220:221], s[48:49], 0, v[138:139]
	s_mov_b32 m0, s51
	s_nop 0
	global_load_lds_dwordx4 v[220:221], off
	s_mov_b32 m0, s52
	s_nop 0
	global_load_lds_dwordx4 v[222:223], off
	s_waitcnt vmcnt(8)
	s_waitcnt lgkmcnt(0)
	s_setprio 1
	s_barrier
; #define PG8_STAGE(bufoff, gbase, voff) do { _Pragma("unroll") for (int _i = 0; _i < 2; ++_i) \
;         __builtin_amdgcn_global_load_lds((const unsigned*)((const char*)(gbase) + (voff)[_i]), (PG8_LAS unsigned*)(lds + (bufoff) + ldsw + _i * 8192), 16, 0, 0); } while (0)
; #define PG8_LDA(dst, b, h) do { _Pragma("unroll") for (int m = 0; m < 4; ++m) _Pragma("unroll") for (int k = 0; k < 2; ++k) dst[m][k] = *(const PG8_LAS bf16x8*)(lds + PG8_SA(b, h) + aoff + m * 2048 + k * 1024); } while (0)
; #define PG8_LDB(dst, b, h) do { _Pragma("unroll") for (int n = 0; n < 2; ++n) _Pragma("unroll") for (int k = 0; k < 2; ++k) dst[n][k] = *(const PG8_LAS bf16x8*)(lds + PG8_SB(b, h) + boff + n * 2048 + k * 1024); } while (0)
; #define PG8_MMA(ai, bj, At, Bt) do { __builtin_amdgcn_s_setprio(1); _Pragma("unroll") for (int m = 0; m < 4; ++m) _Pragma("unroll") for (int n = 0; n < 2; ++n) _Pragma("unroll") for (int k = 0; k < 2; ++k) \
;         acc[ai][bj][m][n] = __builtin_amdgcn_mfma_f32_16x16x32_bf16(Bt[n][k], At[m][k], acc[ai][bj][m][n], 0, 0, 0); __builtin_amdgcn_s_setprio(0); } while (0)
; #define PG8_WAIT_V(n) asm volatile("s_waitcnt vmcnt(" #n ")" ::: "memory")
; #define PG8_WAIT_L(n) asm volatile("s_waitcnt lgkmcnt(" #n ")" ::: "memory")
; #define PG8_BAR __builtin_amdgcn_s_barrier()
; #define PG8_SCHED __builtin_amdgcn_sched_barrier(0)
; template <class Epi, class Sched, bool ALIGN_EPI = false, bool SP2 = false>
; __device__ __forceinline__ void gemm_phase(PG8_LAS unsigned char* lds, const Gemm g, const Sched& S, const Epi& E) {
;     ...
;             PG8_WAIT_V(8); PG8_WAIT_L(0); PG8_BAR; PG8_MMA(1, 0, At, B0); PG8_MMA(1, 1, At, B1); PG8_BAR; PG8_SCHED;
;             PG8_LDB(B0, 1, 0); PG8_LDB(B1, 1, 1); PG8_SCHED; PG8_LDA(At, 1, 0); PG8_STAGE(PG8_SA(0, 1), a2 + hstep, voffA);
;             PG8_WAIT_V(8); PG8_WAIT_L(0); PG8_BAR; PG8_MMA(0, 0, At, B0); PG8_MMA(0, 1, At, B1); PG8_BAR; PG8_SCHED;
	v_mfma_f32_16x16x32_bf16 v[60:63], v[128:131], v[182:185], v[60:63]
	v_mfma_f32_16x16x32_bf16 v[52:55], v[158:161], v[182:185], v[52:55]
	v_mfma_f32_16x16x32_bf16 v[44:47], v[128:131], v[194:197], v[44:47]
	v_mfma_f32_16x16x32_bf16 v[36:39], v[158:161], v[194:197], v[36:39]
	v_mfma_f32_16x16x32_bf16 v[28:31], v[128:131], v[202:205], v[28:31]
	v_mfma_f32_16x16x32_bf16 v[20:23], v[158:161], v[202:205], v[20:23]
	v_mfma_f32_16x16x32_bf16 v[12:15], v[128:131], v[210:213], v[12:15]
	v_mfma_f32_16x16x32_bf16 v[4:7], v[158:161], v[210:213], v[4:7]
	v_mfma_f32_16x16x32_bf16 v[60:63], v[154:157], v[186:189], v[60:63]
	v_mfma_f32_16x16x32_bf16 v[52:55], v[162:165], v[186:189], v[52:55]
	v_mfma_f32_16x16x32_bf16 v[44:47], v[154:157], v[198:201], v[44:47]
	v_mfma_f32_16x16x32_bf16 v[36:39], v[162:165], v[198:201], v[36:39]
	v_mfma_f32_16x16x32_bf16 v[28:31], v[154:157], v[206:209], v[28:31]
	v_mfma_f32_16x16x32_bf16 v[20:23], v[162:165], v[206:209], v[20:23]
	v_mfma_f32_16x16x32_bf16 v[12:15], v[154:157], v[214:217], v[12:15]
	v_mfma_f32_16x16x32_bf16 v[4:7], v[162:165], v[214:217], v[4:7]
	v_mfma_f32_16x16x32_bf16 v[56:59], v[166:169], v[182:185], v[56:59]
	v_mfma_f32_16x16x32_bf16 v[48:51], v[174:177], v[182:185], v[48:51]
	v_mfma_f32_16x16x32_bf16 v[40:43], v[166:169], v[194:197], v[40:43]
	v_mfma_f32_16x16x32_bf16 v[32:35], v[174:177], v[194:197], v[32:35]
	v_mfma_f32_16x16x32_bf16 v[24:27], v[166:169], v[202:205], v[24:27]
	v_mfma_f32_16x16x32_bf16 v[16:19], v[174:177], v[202:205], v[16:19]
	v_mfma_f32_16x16x32_bf16 v[8:11], v[166:169], v[210:213], v[8:11]
	v_mfma_f32_16x16x32_bf16 v[0:3], v[174:177], v[210:213], v[0:3]
	v_mfma_f32_16x16x32_bf16 v[56:59], v[170:173], v[186:189], v[56:59]
	v_mfma_f32_16x16x32_bf16 v[48:51], v[178:181], v[186:189], v[48:51]
	v_mfma_f32_16x16x32_bf16 v[40:43], v[170:173], v[198:201], v[40:43]
	v_mfma_f32_16x16x32_bf16 v[32:35], v[178:181], v[198:201], v[32:35]
	v_mfma_f32_16x16x32_bf16 v[24:27], v[170:173], v[206:209], v[24:27]
	v_mfma_f32_16x16x32_bf16 v[16:19], v[178:181], v[206:209], v[16:19]
	v_mfma_f32_16x16x32_bf16 v[8:11], v[170:173], v[214:217], v[8:11]
	v_mfma_f32_16x16x32_bf16 v[0:3], v[178:181], v[214:217], v[0:3]
	s_barrier
	s_setprio 0
	s_add_i32 s64, 0, 0x18000
	v_add_u32_e32 v146, s64, v149
	s_add_i32 s65, 0, 0x1c000
	ds_read_b128 v[128:131], v146
	ds_read_b128 v[154:157], v146 offset:1024
	ds_read_b128 v[158:161], v146 offset:2048
	ds_read_b128 v[162:165], v146 offset:3072
	v_add_u32_e32 v146, s65, v149
	ds_read_b128 v[166:169], v146
	ds_read_b128 v[170:173], v146 offset:1024
	ds_read_b128 v[174:177], v146 offset:2048
	ds_read_b128 v[178:181], v146 offset:3072
	s_add_u32 s10, s48, 0x40000
	s_addc_u32 s11, s49, 0
	s_mov_b32 m0, s53
	v_lshl_add_u64 v[224:225], s[10:11], 0, v[138:139]
	ds_read_b128 v[182:185], v153 offset:32768
	ds_read_b128 v[186:189], v153 offset:33792
	ds_read_b128 v[194:197], v153 offset:34816
	ds_read_b128 v[198:201], v153 offset:35840
	ds_read_b128 v[202:205], v153 offset:36864
	ds_read_b128 v[206:209], v153 offset:37888
	ds_read_b128 v[210:213], v153 offset:38912
	ds_read_b128 v[214:217], v153 offset:39936
	global_load_lds_dwordx4 v[224:225], off
	v_lshl_add_u64 v[224:225], s[10:11], 0, v[134:135]
	s_mov_b32 m0, s54
	s_nop 0
	global_load_lds_dwordx4 v[224:225], off
	s_waitcnt vmcnt(8)
	s_waitcnt lgkmcnt(0)
	s_setprio 1
	s_barrier
	v_mfma_f32_16x16x32_bf16 v[124:127], v[128:131], v[182:185], v[124:127]
	v_mfma_f32_16x16x32_bf16 v[116:119], v[158:161], v[182:185], v[116:119]
	v_mfma_f32_16x16x32_bf16 v[108:111], v[128:131], v[194:197], v[108:111]
	v_mfma_f32_16x16x32_bf16 v[100:103], v[158:161], v[194:197], v[100:103]
	v_mfma_f32_16x16x32_bf16 v[92:95], v[128:131], v[202:205], v[92:95]
	v_mfma_f32_16x16x32_bf16 v[84:87], v[158:161], v[202:205], v[84:87]
	v_mfma_f32_16x16x32_bf16 v[76:79], v[128:131], v[210:213], v[76:79]
	v_mfma_f32_16x16x32_bf16 v[68:71], v[158:161], v[210:213], v[68:71]
	v_mfma_f32_16x16x32_bf16 v[124:127], v[154:157], v[186:189], v[124:127]
	v_mfma_f32_16x16x32_bf16 v[116:119], v[162:165], v[186:189], v[116:119]
	v_mfma_f32_16x16x32_bf16 v[108:111], v[154:157], v[198:201], v[108:111]
	v_mfma_f32_16x16x32_bf16 v[100:103], v[162:165], v[198:201], v[100:103]
	v_mfma_f32_16x16x32_bf16 v[92:95], v[154:157], v[206:209], v[92:95]
	v_mfma_f32_16x16x32_bf16 v[84:87], v[162:165], v[206:209], v[84:87]
	v_mfma_f32_16x16x32_bf16 v[76:79], v[154:157], v[214:217], v[76:79]
	v_mfma_f32_16x16x32_bf16 v[68:71], v[162:165], v[214:217], v[68:71]
	v_mfma_f32_16x16x32_bf16 v[120:123], v[166:169], v[182:185], v[120:123]
	v_mfma_f32_16x16x32_bf16 v[112:115], v[174:177], v[182:185], v[112:115]
	v_mfma_f32_16x16x32_bf16 v[104:107], v[166:169], v[194:197], v[104:107]
	v_mfma_f32_16x16x32_bf16 v[96:99], v[174:177], v[194:197], v[96:99]
	v_mfma_f32_16x16x32_bf16 v[88:91], v[166:169], v[202:205], v[88:91]
	v_mfma_f32_16x16x32_bf16 v[80:83], v[174:177], v[202:205], v[80:83]
	v_mfma_f32_16x16x32_bf16 v[72:75], v[166:169], v[210:213], v[72:75]
	v_mfma_f32_16x16x32_bf16 v[64:67], v[174:177], v[210:213], v[64:67]
	v_mfma_f32_16x16x32_bf16 v[120:123], v[170:173], v[186:189], v[120:123]
	v_mfma_f32_16x16x32_bf16 v[112:115], v[178:181], v[186:189], v[112:115]
	v_mfma_f32_16x16x32_bf16 v[104:107], v[170:173], v[198:201], v[104:107]
	v_mfma_f32_16x16x32_bf16 v[96:99], v[178:181], v[198:201], v[96:99]
	v_mfma_f32_16x16x32_bf16 v[88:91], v[170:173], v[206:209], v[88:91]
	v_mfma_f32_16x16x32_bf16 v[80:83], v[178:181], v[206:209], v[80:83]
	v_mfma_f32_16x16x32_bf16 v[72:75], v[170:173], v[214:217], v[72:75]
	v_mfma_f32_16x16x32_bf16 v[64:67], v[178:181], v[214:217], v[64:67]
	s_barrier
; #define PG8_STAGE(bufoff, gbase, voff) do { _Pragma("unroll") for (int _i = 0; _i < 2; ++_i) \
;         __builtin_amdgcn_global_load_lds((const unsigned*)((const char*)(gbase) + (voff)[_i]), (PG8_LAS unsigned*)(lds + (bufoff) + ldsw + _i * 8192), 16, 0, 0); } while (0)
; #define PG8_LDA(dst, b, h) do { _Pragma("unroll") for (int m = 0; m < 4; ++m) _Pragma("unroll") for (int k = 0; k < 2; ++k) dst[m][k] = *(const PG8_LAS bf16x8*)(lds + PG8_SA(b, h) + aoff + m * 2048 + k * 1024); } while (0)
; #define PG8_MMA(ai, bj, At, Bt) do { __builtin_amdgcn_s_setprio(1); _Pragma("unroll") for (int m = 0; m < 4; ++m) _Pragma("unroll") for (int n = 0; n < 2; ++n) _Pragma("unroll") for (int k = 0; k < 2; ++k) \
;         acc[ai][bj][m][n] = __builtin_amdgcn_mfma_f32_16x16x32_bf16(Bt[n][k], At[m][k], acc[ai][bj][m][n], 0, 0, 0); __builtin_amdgcn_s_setprio(0); } while (0)
; #define PG8_WAIT_V(n) asm volatile("s_waitcnt vmcnt(" #n ")" ::: "memory")
; #define PG8_WAIT_L(n) asm volatile("s_waitcnt lgkmcnt(" #n ")" ::: "memory")
; #define PG8_BAR __builtin_amdgcn_s_barrier()
; #define PG8_SCHED __builtin_amdgcn_sched_barrier(0)
; template <class Epi, class Sched, bool ALIGN_EPI = false, bool SP2 = false>
; __device__ __forceinline__ void gemm_phase(PG8_LAS unsigned char* lds, const Gemm g, const Sched& S, const Epi& E) {
;     ...
;         for (int t = 0; t < nt; t += 2) {
;             const bool last = (t == nt - 2);
;             const char* a1 = cA + (size_t)(t + 1) * kstep;
;             const char* a2 = last ? nA : cA + (size_t)(t + 2) * kstep; const char* b2 = last ? nB : cB + (size_t)(t + 2) * kstep;
;             const char* a3 = a2 + kstep; const char* b3 = b2 + kstep;
;     ...
;             PG8_LDA(At, 1, 1); PG8_STAGE(PG8_SB(1, 0), b3, voffB); PG8_STAGE(PG8_SB(1, 1), b3 + hstep, voffB); PG8_STAGE(PG8_SA(1, 0), a3, voffA);
;             PG8_WAIT_V(8); PG8_WAIT_L(0); PG8_BAR; PG8_MMA(1, 0, At, B0); PG8_MMA(1, 1, At, B1); PG8_BAR; PG8_SCHED;
	s_setprio 0
	s_add_i32 s10, s64, s19
	v_lshl_add_u64 v[190:191], v[190:191], 0, s[36:37]
	s_mov_b32 m0, s10
	ds_read_b128 v[182:185], v153 offset:49152
	ds_read_b128 v[186:189], v153 offset:50176
	ds_read_b128 v[194:197], v153 offset:51200
	ds_read_b128 v[198:201], v153 offset:52224
	ds_read_b128 v[202:205], v153 offset:53248
	ds_read_b128 v[206:209], v153 offset:54272
	ds_read_b128 v[210:213], v153 offset:55296
	ds_read_b128 v[214:217], v153 offset:56320
	global_load_lds_dwordx4 v[190:191], off
	s_add_i32 m0, s10, 0x2000
	s_add_u32 s10, s46, 0x40080
	v_lshl_add_u64 v[190:191], v[218:219], 0, s[36:37]
	s_addc_u32 s11, s47, 0
	s_add_i32 s46, s65, s19
	global_load_lds_dwordx4 v[190:191], off
	v_lshl_add_u64 v[190:191], s[10:11], 0, v[136:137]
	s_mov_b32 m0, s46
	s_nop 0
	global_load_lds_dwordx4 v[190:191], off
	v_lshl_add_u64 v[190:191], s[10:11], 0, v[132:133]
	s_add_i32 m0, s46, 0x2000
	s_nop 0
	global_load_lds_dwordx4 v[190:191], off
	v_lshl_add_u64 v[190:191], v[220:221], 0, s[36:37]
	s_mov_b32 m0, s20
	s_nop 0
	global_load_lds_dwordx4 v[190:191], off
	v_lshl_add_u64 v[190:191], v[222:223], 0, s[36:37]
	s_mov_b32 m0, s55
	s_nop 0
	global_load_lds_dwordx4 v[190:191], off
	s_waitcnt vmcnt(8)
	s_waitcnt lgkmcnt(0)
	s_setprio 1
	s_barrier
	v_mfma_f32_16x16x32_bf16 v[60:63], v[128:131], v[182:185], v[60:63]
	v_mfma_f32_16x16x32_bf16 v[52:55], v[158:161], v[182:185], v[52:55]
	v_mfma_f32_16x16x32_bf16 v[44:47], v[128:131], v[194:197], v[44:47]
	v_mfma_f32_16x16x32_bf16 v[36:39], v[158:161], v[194:197], v[36:39]
	v_mfma_f32_16x16x32_bf16 v[28:31], v[128:131], v[202:205], v[28:31]
	v_mfma_f32_16x16x32_bf16 v[20:23], v[158:161], v[202:205], v[20:23]
	v_mfma_f32_16x16x32_bf16 v[12:15], v[128:131], v[210:213], v[12:15]
	v_mfma_f32_16x16x32_bf16 v[4:7], v[158:161], v[210:213], v[4:7]
	v_mfma_f32_16x16x32_bf16 v[60:63], v[154:157], v[186:189], v[60:63]
	v_mfma_f32_16x16x32_bf16 v[52:55], v[162:165], v[186:189], v[52:55]
	v_mfma_f32_16x16x32_bf16 v[44:47], v[154:157], v[198:201], v[44:47]
	v_mfma_f32_16x16x32_bf16 v[36:39], v[162:165], v[198:201], v[36:39]
	v_mfma_f32_16x16x32_bf16 v[28:31], v[154:157], v[206:209], v[28:31]
	v_mfma_f32_16x16x32_bf16 v[20:23], v[162:165], v[206:209], v[20:23]
	v_mfma_f32_16x16x32_bf16 v[12:15], v[154:157], v[214:217], v[12:15]
	v_mfma_f32_16x16x32_bf16 v[4:7], v[162:165], v[214:217], v[4:7]
	v_mfma_f32_16x16x32_bf16 v[56:59], v[166:169], v[182:185], v[56:59]
	v_mfma_f32_16x16x32_bf16 v[48:51], v[174:177], v[182:185], v[48:51]
	v_mfma_f32_16x16x32_bf16 v[40:43], v[166:169], v[194:197], v[40:43]
	v_mfma_f32_16x16x32_bf16 v[32:35], v[174:177], v[194:197], v[32:35]
	v_mfma_f32_16x16x32_bf16 v[24:27], v[166:169], v[202:205], v[24:27]
	v_mfma_f32_16x16x32_bf16 v[16:19], v[174:177], v[202:205], v[16:19]
	v_mfma_f32_16x16x32_bf16 v[8:11], v[166:169], v[210:213], v[8:11]
	v_mfma_f32_16x16x32_bf16 v[0:3], v[174:177], v[210:213], v[0:3]
	v_mfma_f32_16x16x32_bf16 v[56:59], v[170:173], v[186:189], v[56:59]
	v_mfma_f32_16x16x32_bf16 v[48:51], v[178:181], v[186:189], v[48:51]
	v_mfma_f32_16x16x32_bf16 v[40:43], v[170:173], v[198:201], v[40:43]
	v_mfma_f32_16x16x32_bf16 v[32:35], v[178:181], v[198:201], v[32:35]
	v_mfma_f32_16x16x32_bf16 v[24:27], v[170:173], v[206:209], v[24:27]
	v_mfma_f32_16x16x32_bf16 v[16:19], v[178:181], v[206:209], v[16:19]
	v_mfma_f32_16x16x32_bf16 v[8:11], v[170:173], v[214:217], v[8:11]
	v_mfma_f32_16x16x32_bf16 v[0:3], v[178:181], v[214:217], v[0:3]
	s_cbranch_vccnz .Llast2_g4
	s_barrier
	s_setprio 0
	s_add_i32 s63, s63, 2
	s_add_u32 s44, s44, 0x100
	s_addc_u32 s45, s45, 0
	s_add_u32 s61, s61, 0x100
	s_addc_u32 s62, s62, 0
	s_cmp_gt_u32 s63, 13
	s_branch .LBB0_577
